# skinny GEMM K loops: operand fragments fetched row-contiguous by LDS-DMA into wave-private LDS ring (6 k-steps in flight), fold-vector partial sums loaded together
# speedup vs baseline: 1.1078x; 1.0386x over previous
; template <int KSPLIT, class F>
; __device__ __forceinline__ void skinny_gemm(const bf16_t* A, const bf16_t* Bt, int N, int K, const F& f, LAS unsigned char* lds, int bx, int G, int wave) {
;     ...
;     for (int t = bx; t < ntiles; t += G) {
;         const int rg = t % RG, n0 = (t / RG) * 16;
;         const int mt = rg * MTW + (wave % MTW), kq = wave / MTW;
;         const bf16_t* ap = A + (size_t)(MP + 16 * mt + fr) * K + kq * klen + 8 * fq;
;         const bf16_t* bp = Bt + (size_t)(n0 + fr) * K + kq * klen + 8 * fq;
;         f32x4 acc = (f32x4){0.f, 0.f, 0.f, 0.f};
; #pragma unroll 16
;         for (int k = 0; k < klen; k += 32) {
;             const bf16x8 af = *(const bf16x8*)(ap + k), bf = *(const bf16x8*)(bp + k);
;             acc = __builtin_amdgcn_mfma_f32_16x16x32_bf16(bf, af, acc, 0, 0, 0);
.LBB0_1486:
	v_lshl_add_u64 v[32:33], v[28:29], 0, v[22:23]
	v_lshl_add_u64 v[34:35], v[30:31], 0, v[22:23]
	v_readlane_b32 s100, v251, 60
	s_mul_i32 s100, s100, 0x3000
	s_add_i32 s100, s100, 0x2000
	v_lshrrev_b32_e32 v202, 2, v219
	v_and_b32_e32 v203, 15, v219
	v_lshrrev_b32_e32 v201, 4, v219
	v_sub_u32_e32 v202, v202, v203
	v_lshlrev_b32_e32 v202, 11, v202
	v_and_b32_e32 v204, 3, v219
	v_xor_b32_e32 v204, v204, v201
	v_sub_u32_e32 v204, v204, v201
	v_lshl_add_u32 v202, v204, 4, v202
	v_lshrrev_b32_e32 v204, 2, v203
	v_xor_b32_e32 v204, v204, v201
	v_lshlrev_b32_e32 v200, 6, v203
	v_lshl_add_u32 v200, v204, 4, v200
	v_add_u32_e32 v200, s100, v200
	v_ashrrev_i32_e32 v203, 31, v202
	v_lshl_add_u64 v[196:197], v[202:203], 0, v[32:33]
	v_lshl_add_u64 v[198:199], v[202:203], 0, v[34:35]
	s_add_i32 m0, s100, 512
	s_nop 0
	global_load_lds_dwordx4 v[196:197], off offset:-512
	s_add_i32 m0, s100, 1024
	s_nop 0
	global_load_lds_dwordx4 v[198:199], off
	s_add_i32 m0, s100, 3008
	s_nop 0
	global_load_lds_dwordx4 v[198:199], off offset:64
	s_add_i32 m0, s100, 2496
	s_nop 0
	global_load_lds_dwordx4 v[196:197], off offset:-448
	s_add_i32 m0, s100, 4992
	s_nop 0
	global_load_lds_dwordx4 v[198:199], off offset:128
	s_add_i32 m0, s100, 4480
	s_nop 0
	global_load_lds_dwordx4 v[196:197], off offset:-384
	s_add_i32 m0, s100, 6976
	s_nop 0
	global_load_lds_dwordx4 v[198:199], off offset:192
	s_add_i32 m0, s100, 6464
	s_nop 0
	global_load_lds_dwordx4 v[196:197], off offset:-320
	s_add_i32 m0, s100, 8960
	s_nop 0
	global_load_lds_dwordx4 v[198:199], off offset:256
	s_add_i32 m0, s100, 8448
	s_nop 0
	global_load_lds_dwordx4 v[196:197], off offset:-256
	s_add_i32 m0, s100, 10944
	s_nop 0
	global_load_lds_dwordx4 v[198:199], off offset:320
	s_add_i32 m0, s100, 10432
	s_nop 0
	global_load_lds_dwordx4 v[196:197], off offset:-192
	s_waitcnt vmcnt(10)
	ds_read_b128 v[180:183], v200 offset:0
	ds_read_b128 v[184:187], v200 offset:1024
	s_waitcnt vmcnt(8)
	ds_read_b128 v[188:191], v200 offset:2048
	ds_read_b128 v[192:195], v200 offset:3072
	s_waitcnt lgkmcnt(2)
	v_mfma_f32_16x16x32_bf16 v[4:7], v[180:183], v[184:187], v[4:7]
	s_add_i32 m0, s100, 640
	s_nop 0
	global_load_lds_dwordx4 v[198:199], off offset:384
	s_add_i32 m0, s100, 128
	s_nop 0
	global_load_lds_dwordx4 v[196:197], off offset:-128
	s_waitcnt vmcnt(8)
	ds_read_b128 v[180:183], v200 offset:4096
	ds_read_b128 v[184:187], v200 offset:5120
	s_waitcnt lgkmcnt(2)
	v_mfma_f32_16x16x32_bf16 v[4:7], v[188:191], v[192:195], v[4:7]
	s_add_i32 m0, s100, 2624
	s_nop 0
	global_load_lds_dwordx4 v[198:199], off offset:448
	s_add_i32 m0, s100, 2112
	s_nop 0
	global_load_lds_dwordx4 v[196:197], off offset:-64
	s_waitcnt vmcnt(8)
	ds_read_b128 v[188:191], v200 offset:6144
	ds_read_b128 v[192:195], v200 offset:7168
	s_waitcnt lgkmcnt(2)
	v_mfma_f32_16x16x32_bf16 v[4:7], v[180:183], v[184:187], v[4:7]
	s_add_i32 m0, s100, 4608
	s_nop 0
	global_load_lds_dwordx4 v[198:199], off offset:512
	s_add_i32 m0, s100, 4096
	s_nop 0
	global_load_lds_dwordx4 v[196:197], off
	s_waitcnt vmcnt(8)
	ds_read_b128 v[180:183], v200 offset:8192
	ds_read_b128 v[184:187], v200 offset:9216
	s_waitcnt lgkmcnt(2)
	v_mfma_f32_16x16x32_bf16 v[4:7], v[188:191], v[192:195], v[4:7]
	s_add_i32 m0, s100, 6592
	s_nop 0
	global_load_lds_dwordx4 v[198:199], off offset:576
	s_add_i32 m0, s100, 6080
	s_nop 0
	global_load_lds_dwordx4 v[196:197], off offset:64
	s_waitcnt vmcnt(8)
	ds_read_b128 v[188:191], v200 offset:10240
	ds_read_b128 v[192:195], v200 offset:11264
	s_waitcnt lgkmcnt(2)
	v_mfma_f32_16x16x32_bf16 v[4:7], v[180:183], v[184:187], v[4:7]
	s_add_i32 m0, s100, 8576
	s_nop 0
	global_load_lds_dwordx4 v[198:199], off offset:640
	s_add_i32 m0, s100, 8064
	s_nop 0
	global_load_lds_dwordx4 v[196:197], off offset:128
	s_waitcnt vmcnt(8)
	ds_read_b128 v[180:183], v200 offset:0
	ds_read_b128 v[184:187], v200 offset:1024
	s_waitcnt lgkmcnt(2)
	v_mfma_f32_16x16x32_bf16 v[4:7], v[188:191], v[192:195], v[4:7]
	s_add_i32 m0, s100, 10560
	s_nop 0
	global_load_lds_dwordx4 v[198:199], off offset:704
	s_add_i32 m0, s100, 10048
	s_nop 0
	global_load_lds_dwordx4 v[196:197], off offset:192
	s_waitcnt vmcnt(8)
	ds_read_b128 v[188:191], v200 offset:2048
	ds_read_b128 v[192:195], v200 offset:3072
	s_waitcnt lgkmcnt(2)
	v_mfma_f32_16x16x32_bf16 v[4:7], v[180:183], v[184:187], v[4:7]
	s_add_i32 m0, s100, 256
	s_nop 0
	global_load_lds_dwordx4 v[198:199], off offset:768
	s_add_i32 m0, s100, -256
	s_nop 0
	global_load_lds_dwordx4 v[196:197], off offset:256
	s_waitcnt vmcnt(8)
	ds_read_b128 v[180:183], v200 offset:4096
	ds_read_b128 v[184:187], v200 offset:5120
	s_waitcnt lgkmcnt(2)
	v_mfma_f32_16x16x32_bf16 v[4:7], v[188:191], v[192:195], v[4:7]
	s_add_i32 m0, s100, 2240
	s_nop 0
	global_load_lds_dwordx4 v[198:199], off offset:832
	s_add_i32 m0, s100, 1728
	s_nop 0
	global_load_lds_dwordx4 v[196:197], off offset:320
	s_waitcnt vmcnt(8)
	ds_read_b128 v[188:191], v200 offset:6144
	ds_read_b128 v[192:195], v200 offset:7168
	s_waitcnt lgkmcnt(2)
	v_mfma_f32_16x16x32_bf16 v[4:7], v[180:183], v[184:187], v[4:7]
	s_add_i32 m0, s100, 4224
	s_nop 0
	global_load_lds_dwordx4 v[198:199], off offset:896
	s_add_i32 m0, s100, 3712
	s_nop 0
	global_load_lds_dwordx4 v[196:197], off offset:384
	s_waitcnt vmcnt(8)
	ds_read_b128 v[180:183], v200 offset:8192
	ds_read_b128 v[184:187], v200 offset:9216
	s_waitcnt lgkmcnt(2)
	v_mfma_f32_16x16x32_bf16 v[4:7], v[188:191], v[192:195], v[4:7]
	s_add_i32 m0, s100, 6208
	s_nop 0
	global_load_lds_dwordx4 v[198:199], off offset:960
	s_add_i32 m0, s100, 5696
	s_nop 0
	global_load_lds_dwordx4 v[196:197], off offset:448
	s_waitcnt vmcnt(8)
; template <int KSPLIT, class F>
; __device__ __forceinline__ void skinny_gemm(const bf16_t* A, const bf16_t* Bt, int N, int K, const F& f, LAS unsigned char* lds, int bx, int G, int wave) {
;     ...
; #pragma unroll 16
;         for (int k = 0; k < klen; k += 32) {
;             const bf16x8 af = *(const bf16x8*)(ap + k), bf = *(const bf16x8*)(bp + k);
;             acc = __builtin_amdgcn_mfma_f32_16x16x32_bf16(bf, af, acc, 0, 0, 0);
;         }
	ds_read_b128 v[188:191], v200 offset:10240
	ds_read_b128 v[192:195], v200 offset:11264
	s_waitcnt lgkmcnt(2)
	v_mfma_f32_16x16x32_bf16 v[4:7], v[180:183], v[184:187], v[4:7]
	s_add_i32 m0, s100, 7680
	s_nop 0
	global_load_lds_dwordx4 v[196:197], off offset:512
	s_add_i32 m0, s100, 8192
	s_nop 0
	global_load_lds_dwordx4 v[198:199], off offset:1024
	s_waitcnt vmcnt(8)
	ds_read_b128 v[180:183], v200 offset:0
	ds_read_b128 v[184:187], v200 offset:1024
	s_waitcnt lgkmcnt(2)
	v_mfma_f32_16x16x32_bf16 v[4:7], v[188:191], v[192:195], v[4:7]
	s_add_i32 m0, s100, 10176
	s_nop 0
	global_load_lds_dwordx4 v[198:199], off offset:1088
	s_add_i32 m0, s100, 9664
	s_nop 0
	global_load_lds_dwordx4 v[196:197], off offset:576
	s_waitcnt vmcnt(8)
	ds_read_b128 v[188:191], v200 offset:2048
	ds_read_b128 v[192:195], v200 offset:3072
	s_waitcnt lgkmcnt(2)
	v_mfma_f32_16x16x32_bf16 v[4:7], v[180:183], v[184:187], v[4:7]
	s_add_i32 m0, s100, -128
	s_nop 0
	global_load_lds_dwordx4 v[198:199], off offset:1152
	s_add_i32 m0, s100, -640
	s_nop 0
	global_load_lds_dwordx4 v[196:197], off offset:640
	s_waitcnt vmcnt(8)
	ds_read_b128 v[180:183], v200 offset:4096
	ds_read_b128 v[184:187], v200 offset:5120
	s_waitcnt lgkmcnt(2)
	v_mfma_f32_16x16x32_bf16 v[4:7], v[188:191], v[192:195], v[4:7]
	s_add_i32 m0, s100, 1856
	s_nop 0
	global_load_lds_dwordx4 v[198:199], off offset:1216
	s_add_i32 m0, s100, 1344
	s_nop 0
	global_load_lds_dwordx4 v[196:197], off offset:704
	s_waitcnt vmcnt(8)
	ds_read_b128 v[188:191], v200 offset:6144
	ds_read_b128 v[192:195], v200 offset:7168
	s_waitcnt lgkmcnt(2)
	v_mfma_f32_16x16x32_bf16 v[4:7], v[180:183], v[184:187], v[4:7]
	s_add_i32 m0, s100, 3840
	s_nop 0
	global_load_lds_dwordx4 v[198:199], off offset:1280
	s_add_i32 m0, s100, 3328
	s_nop 0
	global_load_lds_dwordx4 v[196:197], off offset:768
	s_waitcnt vmcnt(8)
	ds_read_b128 v[180:183], v200 offset:8192
	ds_read_b128 v[184:187], v200 offset:9216
	s_waitcnt lgkmcnt(2)
	v_mfma_f32_16x16x32_bf16 v[4:7], v[188:191], v[192:195], v[4:7]
	s_add_i32 m0, s100, 5824
	s_nop 0
	global_load_lds_dwordx4 v[198:199], off offset:1344
	s_add_i32 m0, s100, 5312
	s_nop 0
	global_load_lds_dwordx4 v[196:197], off offset:832
	s_waitcnt vmcnt(8)
	ds_read_b128 v[188:191], v200 offset:10240
	ds_read_b128 v[192:195], v200 offset:11264
	s_waitcnt lgkmcnt(2)
	v_mfma_f32_16x16x32_bf16 v[4:7], v[180:183], v[184:187], v[4:7]
	s_add_i32 m0, s100, 7808
	s_nop 0
	global_load_lds_dwordx4 v[198:199], off offset:1408
	s_add_i32 m0, s100, 7296
	s_nop 0
	global_load_lds_dwordx4 v[196:197], off offset:896
	s_waitcnt vmcnt(8)
	ds_read_b128 v[180:183], v200 offset:0
	ds_read_b128 v[184:187], v200 offset:1024
	s_waitcnt lgkmcnt(2)
	v_mfma_f32_16x16x32_bf16 v[4:7], v[188:191], v[192:195], v[4:7]
	s_add_i32 m0, s100, 9792
	s_nop 0
	global_load_lds_dwordx4 v[198:199], off offset:1472
	s_add_i32 m0, s100, 9280
	s_nop 0
	global_load_lds_dwordx4 v[196:197], off offset:960
	s_waitcnt vmcnt(8)
	ds_read_b128 v[188:191], v200 offset:2048
	ds_read_b128 v[192:195], v200 offset:3072
	s_waitcnt lgkmcnt(2)
	v_mfma_f32_16x16x32_bf16 v[4:7], v[180:183], v[184:187], v[4:7]
	s_add_i32 m0, s100, -512
	s_nop 0
	global_load_lds_dwordx4 v[198:199], off offset:1536
	s_add_i32 m0, s100, -1024
	s_nop 0
	global_load_lds_dwordx4 v[196:197], off offset:1024
	s_waitcnt vmcnt(8)
	ds_read_b128 v[180:183], v200 offset:4096
	ds_read_b128 v[184:187], v200 offset:5120
	s_waitcnt lgkmcnt(2)
	v_mfma_f32_16x16x32_bf16 v[4:7], v[188:191], v[192:195], v[4:7]
	s_add_i32 m0, s100, 1472
	s_nop 0
	global_load_lds_dwordx4 v[198:199], off offset:1600
	s_add_i32 m0, s100, 960
	s_nop 0
	global_load_lds_dwordx4 v[196:197], off offset:1088
	s_waitcnt vmcnt(8)
	ds_read_b128 v[188:191], v200 offset:6144
	ds_read_b128 v[192:195], v200 offset:7168
	s_waitcnt lgkmcnt(2)
	v_mfma_f32_16x16x32_bf16 v[4:7], v[180:183], v[184:187], v[4:7]
	s_add_i32 m0, s100, 3456
	s_nop 0
	global_load_lds_dwordx4 v[198:199], off offset:1664
	s_add_i32 m0, s100, 2944
	s_nop 0
	global_load_lds_dwordx4 v[196:197], off offset:1152
	s_waitcnt vmcnt(8)
	ds_read_b128 v[180:183], v200 offset:8192
	ds_read_b128 v[184:187], v200 offset:9216
	s_waitcnt lgkmcnt(2)
	v_mfma_f32_16x16x32_bf16 v[4:7], v[188:191], v[192:195], v[4:7]
	s_add_i32 m0, s100, 5440
	s_nop 0
	global_load_lds_dwordx4 v[198:199], off offset:1728
	s_add_i32 m0, s100, 4928
	s_nop 0
	global_load_lds_dwordx4 v[196:197], off offset:1216
	s_waitcnt vmcnt(8)
	ds_read_b128 v[188:191], v200 offset:10240
	ds_read_b128 v[192:195], v200 offset:11264
	s_waitcnt lgkmcnt(2)
	v_mfma_f32_16x16x32_bf16 v[4:7], v[180:183], v[184:187], v[4:7]
	s_add_i32 m0, s100, 7424
	s_nop 0
	global_load_lds_dwordx4 v[198:199], off offset:1792
	s_add_i32 m0, s100, 6912
	s_nop 0
	global_load_lds_dwordx4 v[196:197], off offset:1280
	s_waitcnt vmcnt(8)
	ds_read_b128 v[180:183], v200 offset:0
	ds_read_b128 v[184:187], v200 offset:1024
	s_waitcnt lgkmcnt(2)
	v_mfma_f32_16x16x32_bf16 v[4:7], v[188:191], v[192:195], v[4:7]
	s_add_i32 m0, s100, 9408
	s_nop 0
	global_load_lds_dwordx4 v[198:199], off offset:1856
	s_add_i32 m0, s100, 8896
	s_nop 0
	global_load_lds_dwordx4 v[196:197], off offset:1344
	s_waitcnt vmcnt(8)
	ds_read_b128 v[188:191], v200 offset:2048
	ds_read_b128 v[192:195], v200 offset:3072
	s_waitcnt lgkmcnt(2)
	v_mfma_f32_16x16x32_bf16 v[4:7], v[180:183], v[184:187], v[4:7]
	s_add_i32 m0, s100, -896
	s_nop 0
	global_load_lds_dwordx4 v[198:199], off offset:1920
	s_add_i32 m0, s100, -1408
	s_nop 0
	global_load_lds_dwordx4 v[196:197], off offset:1408
	s_waitcnt vmcnt(8)
	ds_read_b128 v[180:183], v200 offset:4096
	ds_read_b128 v[184:187], v200 offset:5120
	s_waitcnt lgkmcnt(2)
	v_mfma_f32_16x16x32_bf16 v[4:7], v[188:191], v[192:195], v[4:7]
	s_add_i32 m0, s100, 1088
	s_nop 0
	global_load_lds_dwordx4 v[198:199], off offset:1984
	s_add_i32 m0, s100, 576
	s_nop 0
	global_load_lds_dwordx4 v[196:197], off offset:1472
	s_waitcnt vmcnt(8)
	ds_read_b128 v[188:191], v200 offset:6144
	ds_read_b128 v[192:195], v200 offset:7168
	s_waitcnt lgkmcnt(2)
	v_mfma_f32_16x16x32_bf16 v[4:7], v[180:183], v[184:187], v[4:7]
	s_waitcnt vmcnt(6)
	ds_read_b128 v[180:183], v200 offset:8192
	ds_read_b128 v[184:187], v200 offset:9216
	s_waitcnt lgkmcnt(2)
	v_mfma_f32_16x16x32_bf16 v[4:7], v[188:191], v[192:195], v[4:7]
	s_waitcnt vmcnt(4)
	ds_read_b128 v[188:191], v200 offset:10240
	ds_read_b128 v[192:195], v200 offset:11264
	s_waitcnt lgkmcnt(2)
	v_mfma_f32_16x16x32_bf16 v[4:7], v[180:183], v[184:187], v[4:7]
	s_waitcnt vmcnt(2)
	ds_read_b128 v[180:183], v200 offset:0
	ds_read_b128 v[184:187], v200 offset:1024
	s_waitcnt lgkmcnt(2)
	v_mfma_f32_16x16x32_bf16 v[4:7], v[188:191], v[192:195], v[4:7]
	s_waitcnt vmcnt(0)
	ds_read_b128 v[188:191], v200 offset:2048
	ds_read_b128 v[192:195], v200 offset:3072
	s_waitcnt lgkmcnt(2)
	v_mfma_f32_16x16x32_bf16 v[4:7], v[180:183], v[184:187], v[4:7]
	s_waitcnt lgkmcnt(0)
	v_mfma_f32_16x16x32_bf16 v[4:7], v[188:191], v[192:195], v[4:7]
	s_barrier
; __device__ __forceinline__ void stats_sk(const float* sts, int row, int fq, float& mu, float& rs) {
;     const f32x4* p = (const f32x4*)(sts + (size_t)(row - MP) * 128 + fq * 32);
;     float s1 = 0.f, s2 = 0.f;
; #pragma unroll
;     for (int i = 0; i < 8; ++i) { const f32x4 a = p[i]; s1 += a.x + a.z; s2 += a.y + a.w; }
;     s1 += __shfl_xor(s1, 16); s2 += __shfl_xor(s2, 16); s1 += __shfl_xor(s1, 32); s2 += __shfl_xor(s2, 32);
;     mu = s1 * (1.f / DM); rs = __builtin_amdgcn_rsqf(fmaxf(s2 * (1.f / DM) - mu * mu, 0.f) + LN_EPS);
; }
;     __device__ __forceinline__ void sk(int row, int col, f32x4 v, int fq) const {
;         if (fold) { float mu, rs; stats_sk(sts, row, fq, mu, rs); const f32x4 c1v = *(const f32x4*)(c1 + col), c2v = *(const f32x4*)(c2 + col); v = (v - c1v * mu) * rs + c2v; }
;         float d1 = 0.f, d2 = 0.f; f(row, col, v, fq, d1, d2);
; template <int KSPLIT, class F>
; __device__ __forceinline__ void skinny_gemm(const bf16_t* A, const bf16_t* Bt, int N, int K, const F& f, LAS unsigned char* lds, int bx, int G, int wave) {
;     ...
;         for (int k = 0; k < klen; k += 32) {
;             const bf16x8 af = *(const bf16x8*)(ap + k), bf = *(const bf16x8*)(bp + k);
;             acc = __builtin_amdgcn_mfma_f32_16x16x32_bf16(bf, af, acc, 0, 0, 0);
;         }
	s_nop 0
	v_lshl_add_u32 v28, s2, 4, v3
	s_andn2_b64 vcc, exec, s[96:97]
	s_cbranch_vccnz .LBB0_1489
	global_load_dwordx4 v[30:33], v[0:1], off offset:48
	global_load_dwordx4 v[34:37], v[0:1], off offset:32
	global_load_dwordx4 v[38:41], v[0:1], off offset:16
	global_load_dwordx4 v[42:45], v[0:1], off
	global_load_dwordx4 v[46:49], v[0:1], off offset:112
	global_load_dwordx4 v[50:53], v[0:1], off offset:96
	global_load_dwordx4 v[54:57], v[0:1], off offset:80
	global_load_dwordx4 v[58:61], v[0:1], off offset:64
	v_and_b32_e32 v29, 64, v219
	v_xor_b32_e32 v25, 16, v219
	v_add_u32_e32 v29, 64, v29
	v_cmp_lt_i32_e32 vcc, v25, v29
	v_xor_b32_e32 v62, 32, v219
	v_readlane_b32 s0, v250, 35
	v_cndmask_b32_e32 v25, v219, v25, vcc
	v_lshlrev_b32_e32 v25, 2, v25
	v_cmp_lt_i32_e32 vcc, v62, v29
	v_readlane_b32 s1, v250, 36
	s_waitcnt vmcnt(7)
	v_pk_add_f32 v[30:31], v[30:31], v[32:33]
	s_waitcnt vmcnt(6)
	v_pk_add_f32 v[34:35], v[34:35], v[36:37]
	s_waitcnt vmcnt(5)
	v_pk_add_f32 v[38:39], v[38:39], v[40:41]
	s_waitcnt vmcnt(4)
	v_pk_add_f32 v[42:43], v[42:43], v[44:45]
	v_cndmask_b32_e32 v29, v219, v62, vcc
	v_pk_add_f32 v[42:43], v[42:43], 0 op_sel_hi:[1,0]
	v_lshlrev_b32_e32 v29, 2, v29
	v_pk_add_f32 v[38:39], v[42:43], v[38:39]
	s_waitcnt vmcnt(0)
	v_pk_add_f32 v[32:33], v[58:59], v[60:61]
	v_pk_add_f32 v[34:35], v[38:39], v[34:35]
	s_nop 0
	v_pk_add_f32 v[30:31], v[34:35], v[30:31]
	s_nop 0
	v_pk_add_f32 v[30:31], v[30:31], v[32:33]
	v_pk_add_f32 v[32:33], v[54:55], v[56:57]
	s_nop 0
	v_pk_add_f32 v[30:31], v[30:31], v[32:33]
	v_pk_add_f32 v[32:33], v[50:51], v[52:53]
	s_nop 0
	v_pk_add_f32 v[30:31], v[30:31], v[32:33]
	v_pk_add_f32 v[32:33], v[46:47], v[48:49]
	s_nop 0
	v_pk_add_f32 v[30:31], v[30:31], v[32:33]
	ds_bpermute_b32 v32, v25, v30
	ds_bpermute_b32 v33, v25, v31
	s_waitcnt lgkmcnt(0)
	v_pk_add_f32 v[30:31], v[30:31], v[32:33]
	ds_bpermute_b32 v32, v29, v30
	ds_bpermute_b32 v33, v29, v31
	v_ashrrev_i32_e32 v29, 31, v28
	v_lshlrev_b64 v[38:39], 2, v[28:29]
	v_lshl_add_u64 v[34:35], s[0:1], 0, v[38:39]
	global_load_dwordx4 v[34:37], v[34:35], off
	v_lshl_add_u64 v[38:39], s[64:65], 0, v[38:39]
	global_load_dwordx4 v[38:41], v[38:39], off
	s_waitcnt lgkmcnt(0)
	v_pk_add_f32 v[30:31], v[30:31], v[32:33]
	s_nop 0
	v_pk_mul_f32 v[32:33], v[30:31], s[82:83] op_sel_hi:[1,0]
	s_nop 0
	v_fma_f32 v25, -v32, v32, v33
	v_max_f32_e32 v25, 0, v25
	v_add_f32_e32 v25, 0x3727c5ac, v25
	v_rsq_f32_e32 v30, v25
	s_waitcnt vmcnt(1)
	v_pk_fma_f32 v[4:5], v[34:35], v[32:33], v[4:5] op_sel_hi:[1,0,1] neg_lo:[1,0,0] neg_hi:[1,0,0]
	v_xor_b32_e32 v35, 0x80000000, v37
	v_xor_b32_e32 v34, 0x80000000, v36
	v_pk_fma_f32 v[6:7], v[34:35], v[32:33], v[6:7] op_sel_hi:[1,0,1]
	s_waitcnt vmcnt(0)
	v_pk_fma_f32 v[4:5], v[4:5], v[30:31], v[38:39] op_sel_hi:[1,0,1]
	v_pk_fma_f32 v[6:7], v[6:7], v[30:31], v[40:41] op_sel_hi:[1,0,1]

; __global__ void __launch_bounds__(NWAVES * 64, 2) mega(Args args) {
;     ...
;                 for (int e = bx * 512 + tid; e < DEPTH * 3 * 2 * 4096; e += G * 512) {
;                     const int lw = e / 8192, rem = e % 8192; const float* p = CVP + (size_t)lw * 16 * 8192 + rem; float a = 0.f;
; #pragma unroll
;                     for (int kb = 0; kb < 16; ++kb) a += p[kb * 8192];
;                     CV[e] = a;
;                 }
.LBB0_1582:
	v_ashrrev_i32_e32 v1, 31, v0
	v_lshrrev_b32_e32 v3, 19, v1
	v_add_u32_e32 v3, v0, v3
	v_ashrrev_i32_e32 v4, 13, v3
	v_mul_i32_i24_e32 v3, 0x2000, v4
	v_ashrrev_i32_e32 v5, 31, v4
	s_waitcnt lgkmcnt(0)
	v_sub_u32_e32 v6, v0, v3
	v_lshlrev_b64 v[4:5], 19, v[4:5]
	v_lshl_add_u64 v[4:5], s[22:23], 0, v[4:5]
	v_ashrrev_i32_e32 v7, 31, v6
	v_lshl_add_u64 v[4:5], v[6:7], 2, v[4:5]
	global_load_dword v180, v[4:5], off
	v_add_co_u32_e32 v196, vcc, 0x8000, v4
	s_nop 1
	v_addc_co_u32_e32 v197, vcc, 0, v5, vcc
	global_load_dword v181, v[196:197], off
	v_add_co_u32_e32 v196, vcc, 0x10000, v4
	s_nop 1
	v_addc_co_u32_e32 v197, vcc, 0, v5, vcc
	global_load_dword v182, v[196:197], off
	v_add_co_u32_e32 v196, vcc, 0x18000, v4
	s_nop 1
	v_addc_co_u32_e32 v197, vcc, 0, v5, vcc
	global_load_dword v183, v[196:197], off
	v_add_co_u32_e32 v196, vcc, 0x20000, v4
	s_nop 1
	v_addc_co_u32_e32 v197, vcc, 0, v5, vcc
	global_load_dword v184, v[196:197], off
	v_add_co_u32_e32 v196, vcc, 0x28000, v4
	s_nop 1
	v_addc_co_u32_e32 v197, vcc, 0, v5, vcc
	global_load_dword v185, v[196:197], off
	v_add_co_u32_e32 v196, vcc, 0x30000, v4
	s_nop 1
	v_addc_co_u32_e32 v197, vcc, 0, v5, vcc
	global_load_dword v186, v[196:197], off
	v_add_co_u32_e32 v196, vcc, 0x38000, v4
	s_nop 1
	v_addc_co_u32_e32 v197, vcc, 0, v5, vcc
	global_load_dword v187, v[196:197], off
	v_add_co_u32_e32 v196, vcc, 0x40000, v4
	s_nop 1
	v_addc_co_u32_e32 v197, vcc, 0, v5, vcc
	global_load_dword v188, v[196:197], off
	v_add_co_u32_e32 v196, vcc, 0x48000, v4
	s_nop 1
	v_addc_co_u32_e32 v197, vcc, 0, v5, vcc
	global_load_dword v189, v[196:197], off
	v_add_co_u32_e32 v196, vcc, 0x50000, v4
	s_nop 1
	v_addc_co_u32_e32 v197, vcc, 0, v5, vcc
	global_load_dword v190, v[196:197], off
	v_add_co_u32_e32 v196, vcc, 0x58000, v4
	s_nop 1
	v_addc_co_u32_e32 v197, vcc, 0, v5, vcc
	global_load_dword v191, v[196:197], off
	v_add_co_u32_e32 v196, vcc, 0x60000, v4
	s_nop 1
	v_addc_co_u32_e32 v197, vcc, 0, v5, vcc
	global_load_dword v192, v[196:197], off
	v_add_co_u32_e32 v196, vcc, 0x68000, v4
	s_nop 1
	v_addc_co_u32_e32 v197, vcc, 0, v5, vcc
	global_load_dword v193, v[196:197], off
	v_add_co_u32_e32 v196, vcc, 0x70000, v4
	s_nop 1
	v_addc_co_u32_e32 v197, vcc, 0, v5, vcc
	global_load_dword v194, v[196:197], off
	v_add_co_u32_e32 v196, vcc, 0x78000, v4
	s_nop 1
	v_addc_co_u32_e32 v197, vcc, 0, v5, vcc
	global_load_dword v195, v[196:197], off
	s_mov_b32 s0, 0xbfff
	s_waitcnt vmcnt(15)
	v_add_f32_e32 v3, 0, v180
	s_waitcnt vmcnt(14)
	v_add_f32_e32 v3, v3, v181
	s_waitcnt vmcnt(13)
	v_add_f32_e32 v3, v3, v182
	s_waitcnt vmcnt(12)
	v_add_f32_e32 v3, v3, v183
	s_waitcnt vmcnt(11)
	v_add_f32_e32 v3, v3, v184
	s_waitcnt vmcnt(10)
	v_add_f32_e32 v3, v3, v185
	s_waitcnt vmcnt(9)
	v_add_f32_e32 v3, v3, v186
	s_waitcnt vmcnt(8)
	v_add_f32_e32 v3, v3, v187
	s_waitcnt vmcnt(7)
	v_add_f32_e32 v3, v3, v188
	s_waitcnt vmcnt(6)
	v_add_f32_e32 v3, v3, v189
	s_waitcnt vmcnt(5)
	v_add_f32_e32 v3, v3, v190
	s_waitcnt vmcnt(4)
	v_add_f32_e32 v3, v3, v191
	s_waitcnt vmcnt(3)
	v_add_f32_e32 v3, v3, v192
	s_waitcnt vmcnt(2)
	v_add_f32_e32 v3, v3, v193
	s_waitcnt vmcnt(1)
	v_add_f32_e32 v3, v3, v194
	s_waitcnt vmcnt(0)
	v_add_f32_e32 v3, v3, v195
	v_lshl_add_u64 v[4:5], v[0:1], 2, s[8:9]
	v_add_u32_e32 v0, s2, v0
	v_cmp_lt_i32_e32 vcc, s0, v0
	s_or_b64 s[36:37], vcc, s[36:37]
	global_store_dword v[4:5], v3, off
	s_andn2_b64 exec, exec, s[36:37]
	s_cbranch_execnz .LBB0_1582

; template <int KSPLIT, class F>
; __device__ __forceinline__ void skinny_gemm(const bf16_t* A, const bf16_t* Bt, int N, int K, const F& f, LAS unsigned char* lds, int bx, int G, int wave) {
;     ...
;     for (int t = bx; t < ntiles; t += G) {
;         const int rg = t % RG, n0 = (t / RG) * 16;
;         const int mt = rg * MTW + (wave % MTW), kq = wave / MTW;
;         const bf16_t* ap = A + (size_t)(MP + 16 * mt + fr) * K + kq * klen + 8 * fq;
;         const bf16_t* bp = Bt + (size_t)(n0 + fr) * K + kq * klen + 8 * fq;
;         f32x4 acc = (f32x4){0.f, 0.f, 0.f, 0.f};
; #pragma unroll 16
;         for (int k = 0; k < klen; k += 32) {
;             const bf16x8 af = *(const bf16x8*)(ap + k), bf = *(const bf16x8*)(bp + k);
;             acc = __builtin_amdgcn_mfma_f32_16x16x32_bf16(bf, af, acc, 0, 0, 0);
;         }
.LBB0_1948:
	s_ashr_i32 s0, s4, 31
	s_lshr_b32 s0, s0, 30
	s_add_i32 s0, s4, s0
	s_ashr_i32 s8, s0, 2
	s_lshl_b32 s1, s8, 7
	v_subrev_u32_e32 v24, s1, v39
	v_add_u32_e32 v4, 0x4000, v24
	v_mov_b32_e32 v5, v2
	s_lshl_b32 s0, s8, 4
	v_lshlrev_b64 v[4:5], 11, v[4:5]
	v_lshl_add_u64 v[16:17], v[0:1], 0, v[4:5]
	v_or_b32_e32 v4, s0, v3
	v_ashrrev_i32_e32 v5, 31, v4
	v_lshlrev_b64 v[4:5], 11, v[4:5]
	v_lshl_add_u64 v[18:19], v[20:21], 0, v[4:5]
	s_waitcnt lgkmcnt(0)
	v_readlane_b32 s10, v253, 39
	v_readlane_b32 s11, v253, 40
	s_andn2_b64 vcc, exec, s[10:11]
	v_readlane_b32 s100, v251, 60
	s_mul_i32 s100, s100, 0x3000
	s_add_i32 s100, s100, 0x2000
	v_lshrrev_b32_e32 v202, 2, v219
	v_and_b32_e32 v203, 15, v219
	v_lshrrev_b32_e32 v201, 4, v219
	v_sub_u32_e32 v202, v202, v203
	v_lshlrev_b32_e32 v202, 11, v202
	v_and_b32_e32 v204, 3, v219
	v_xor_b32_e32 v204, v204, v201
	v_sub_u32_e32 v204, v204, v201
	v_lshl_add_u32 v202, v204, 4, v202
	v_lshrrev_b32_e32 v204, 2, v203
	v_xor_b32_e32 v204, v204, v201
	v_lshlrev_b32_e32 v200, 6, v203
	v_lshl_add_u32 v200, v204, 4, v200
	v_add_u32_e32 v200, s100, v200
	v_ashrrev_i32_e32 v203, 31, v202
	v_lshl_add_u64 v[196:197], v[202:203], 0, v[16:17]
	v_lshl_add_u64 v[198:199], v[202:203], 0, v[18:19]
	s_add_i32 m0, s100, 0
	s_nop 0
	global_load_lds_dwordx4 v[196:197], off
	s_add_i32 m0, s100, 1024
	s_nop 0
	global_load_lds_dwordx4 v[198:199], off
	s_add_i32 m0, s100, 1984
	s_nop 0
	global_load_lds_dwordx4 v[196:197], off offset:64
	s_add_i32 m0, s100, 3008
	s_nop 0
	global_load_lds_dwordx4 v[198:199], off offset:64
	s_add_i32 m0, s100, 3968
	s_nop 0
	global_load_lds_dwordx4 v[196:197], off offset:128
	s_add_i32 m0, s100, 4992
	s_nop 0
	global_load_lds_dwordx4 v[198:199], off offset:128
	s_add_i32 m0, s100, 5952
	s_nop 0
	global_load_lds_dwordx4 v[196:197], off offset:192
	s_add_i32 m0, s100, 6976
	s_nop 0
	global_load_lds_dwordx4 v[198:199], off offset:192
	s_add_i32 m0, s100, 7936
	s_nop 0
	global_load_lds_dwordx4 v[196:197], off offset:256
	s_add_i32 m0, s100, 8960
	s_nop 0
	global_load_lds_dwordx4 v[198:199], off offset:256
	s_add_i32 m0, s100, 9920
	s_nop 0
	global_load_lds_dwordx4 v[196:197], off offset:320
	s_add_i32 m0, s100, 10944
	s_nop 0
	global_load_lds_dwordx4 v[198:199], off offset:320
	s_waitcnt vmcnt(10)
	ds_read_b128 v[180:183], v200 offset:0
	ds_read_b128 v[184:187], v200 offset:1024
	s_waitcnt vmcnt(8)
	ds_read_b128 v[188:191], v200 offset:2048
	ds_read_b128 v[192:195], v200 offset:3072
	s_waitcnt lgkmcnt(2)
	v_mfma_f32_16x16x32_bf16 v[4:7], v[184:187], v[180:183], 0
	s_add_i32 m0, s100, -384
	s_nop 0
	global_load_lds_dwordx4 v[196:197], off offset:384
	s_add_i32 m0, s100, 640
	s_nop 0
	global_load_lds_dwordx4 v[198:199], off offset:384
	s_waitcnt vmcnt(8)
	ds_read_b128 v[180:183], v200 offset:4096
	ds_read_b128 v[184:187], v200 offset:5120
	s_waitcnt lgkmcnt(2)
	v_mfma_f32_16x16x32_bf16 v[4:7], v[192:195], v[188:191], v[4:7]
	s_add_i32 m0, s100, 1600
	s_nop 0
	global_load_lds_dwordx4 v[196:197], off offset:448
	s_add_i32 m0, s100, 2624
	s_nop 0
	global_load_lds_dwordx4 v[198:199], off offset:448
	s_waitcnt vmcnt(8)
	ds_read_b128 v[188:191], v200 offset:6144
	ds_read_b128 v[192:195], v200 offset:7168
	s_waitcnt lgkmcnt(2)
	v_mfma_f32_16x16x32_bf16 v[4:7], v[184:187], v[180:183], v[4:7]
	s_waitcnt vmcnt(6)
	ds_read_b128 v[180:183], v200 offset:8192
	ds_read_b128 v[184:187], v200 offset:9216
	s_waitcnt lgkmcnt(2)
	v_mfma_f32_16x16x32_bf16 v[4:7], v[192:195], v[188:191], v[4:7]
	s_waitcnt vmcnt(4)
	ds_read_b128 v[188:191], v200 offset:10240
	ds_read_b128 v[192:195], v200 offset:11264
	s_waitcnt lgkmcnt(2)
	v_mfma_f32_16x16x32_bf16 v[4:7], v[184:187], v[180:183], v[4:7]
	s_waitcnt vmcnt(2)
	ds_read_b128 v[180:183], v200 offset:0
	ds_read_b128 v[184:187], v200 offset:1024
	s_waitcnt lgkmcnt(2)
	v_mfma_f32_16x16x32_bf16 v[4:7], v[192:195], v[188:191], v[4:7]
	s_waitcnt vmcnt(0)
	ds_read_b128 v[188:191], v200 offset:2048
	ds_read_b128 v[192:195], v200 offset:3072
	s_waitcnt lgkmcnt(2)
	v_mfma_f32_16x16x32_bf16 v[4:7], v[184:187], v[180:183], v[4:7]
	s_waitcnt lgkmcnt(0)
	s_barrier
; #define LAS __attribute__((address_space(3)))
; __device__ __forceinline__ void stats_sk(const float* sts, int row, int fq, float& mu, float& rs) {
;     const f32x4* p = (const f32x4*)(sts + (size_t)(row - MP) * 128 + fq * 32);
;     float s1 = 0.f, s2 = 0.f;
; #pragma unroll
;     for (int i = 0; i < 8; ++i) { const f32x4 a = p[i]; s1 += a.x + a.z; s2 += a.y + a.w; }
;     s1 += __shfl_xor(s1, 16); s2 += __shfl_xor(s2, 16); s1 += __shfl_xor(s1, 32); s2 += __shfl_xor(s2, 32);
;     mu = s1 * (1.f / DM); rs = __builtin_amdgcn_rsqf(fmaxf(s2 * (1.f / DM) - mu * mu, 0.f) + LN_EPS);
;     __device__ __forceinline__ void sk(int row, int col, f32x4 v, int fq) const {
;         float mu = 0.f, rs = 1.f; if (ln) stats_sk(sts_p, row, fq, mu, rs);
; template <int KSPLIT, class F>
; __device__ __forceinline__ void skinny_gemm(const bf16_t* A, const bf16_t* Bt, int N, int K, const F& f, LAS unsigned char* lds, int bx, int G, int wave) {
;     ...
;             acc = __builtin_amdgcn_mfma_f32_16x16x32_bf16(bf, af, acc, 0, 0, 0);
;         }
;         if (KSPLIT > 1) {
;             __syncthreads();
;             *(LAS f32x4*)(lds + wave * 1024 + lane * 16) = acc;
;             __syncthreads();
;             if (kq == 0) {
; #pragma unroll
;                 for (int q = 1; q < KSPLIT; ++q) acc = acc + *(const LAS f32x4*)(lds + (wave + q * MTW) * 1024 + lane * 16);
;                 f.sk(MP + 16 * mt + fr, n0 + 4 * fq, acc, fq);
	v_mfma_f32_16x16x32_bf16 v[4:7], v[192:195], v[188:191], v[4:7]
	s_nop 7
	ds_write_b128 v41, v[4:7]
	s_waitcnt lgkmcnt(0)
	s_barrier
	s_cbranch_vccnz .LBB0_1947
	ds_read_b128 v[16:19], v41 offset:2048
	ds_read_b128 v[12:15], v41 offset:4096
	ds_read_b128 v[8:11], v41 offset:6144
	v_cndmask_b32_e64 v25, 0, 1, s[96:97]
	v_cmp_ne_u32_e64 s[40:41], 1, v25
	s_andn2_b64 vcc, exec, s[96:97]
	v_ashrrev_i32_e32 v25, 31, v24
	s_cbranch_vccnz .LBB0_1951
	v_lshlrev_b64 v[26:27], 9, v[24:25]
	v_lshl_add_u64 v[54:55], v[22:23], 0, v[26:27]
	global_load_dwordx4 v[42:45], v[54:55], off offset:48
	global_load_dwordx4 v[26:29], v[54:55], off offset:32
	global_load_dwordx4 v[46:49], v[54:55], off offset:16
	global_load_dwordx4 v[30:33], v[54:55], off
	s_waitcnt vmcnt(1)
	v_add_f32_e32 v34, v47, v49
	s_waitcnt vmcnt(0)
	v_add_f32_e32 v36, v31, v33
	v_mov_b32_e32 v31, v46
	v_mov_b32_e32 v33, v48
	v_pk_add_f32 v[32:33], v[30:31], v[32:33]
	v_add_f32_e32 v30, v27, v29
	v_mov_b32_e32 v27, v42
	v_mov_b32_e32 v29, v44
	v_pk_add_f32 v[26:27], v[26:27], v[28:29]
	v_add_f32_e32 v28, v43, v45
	global_load_dwordx4 v[42:45], v[54:55], off offset:112
	global_load_dwordx4 v[46:49], v[54:55], off offset:96
	global_load_dwordx4 v[50:53], v[54:55], off offset:80
	s_nop 0
	global_load_dwordx4 v[54:57], v[54:55], off offset:64
	v_and_b32_e32 v31, 64, v219
	v_xor_b32_e32 v29, 16, v219
	v_add_u32_e32 v31, 64, v31
	v_cmp_lt_i32_e32 vcc, v29, v31
	v_mov_b32_e32 v37, v32
	v_pk_add_f32 v[36:37], v[36:37], 0 op_sel_hi:[1,0]
	v_cndmask_b32_e32 v29, v219, v29, vcc
	v_mov_b32_e32 v35, v33
	v_pk_add_f32 v[32:33], v[36:37], v[34:35]
	s_waitcnt vmcnt(0)
	v_add_f32_e32 v58, v55, v57
	v_mov_b32_e32 v57, v52
	v_add_f32_e32 v52, v47, v49
	v_mov_b32_e32 v49, v44
	v_lshlrev_b32_e32 v44, 2, v29
	v_xor_b32_e32 v29, 32, v219
	v_cmp_lt_i32_e32 vcc, v29, v31
	v_mov_b32_e32 v55, v50
	v_mov_b32_e32 v31, v26
	v_cndmask_b32_e32 v29, v219, v29, vcc
	v_pk_add_f32 v[54:55], v[54:55], v[56:57]
	v_mov_b32_e32 v47, v42
	v_add_f32_e32 v42, v43, v45
	v_lshlrev_b32_e32 v45, 2, v29
	v_pk_add_f32 v[30:31], v[32:33], v[30:31]
	v_mov_b32_e32 v29, v27
	v_pk_add_f32 v[26:27], v[30:31], v[28:29]
	v_mov_b32_e32 v59, v54
	v_add_f32_e32 v50, v51, v53
	v_pk_add_f32 v[46:47], v[46:47], v[48:49]
	v_pk_add_f32 v[26:27], v[26:27], v[58:59]
	v_mov_b32_e32 v51, v55
	v_pk_add_f32 v[26:27], v[26:27], v[50:51]
	v_mov_b32_e32 v53, v46
	v_pk_add_f32 v[26:27], v[26:27], v[52:53]
	v_mov_b32_e32 v43, v47
	v_pk_add_f32 v[26:27], v[26:27], v[42:43]
	ds_bpermute_b32 v29, v44, v27
	ds_bpermute_b32 v28, v44, v26
	s_waitcnt lgkmcnt(0)
	v_pk_add_f32 v[26:27], v[26:27], v[28:29]
	ds_bpermute_b32 v29, v45, v27
	ds_bpermute_b32 v28, v45, v26
	s_waitcnt lgkmcnt(0)
	v_pk_add_f32 v[26:27], v[26:27], v[28:29]
	s_nop 0
	v_pk_mul_f32 v[30:31], v[26:27], s[82:83] op_sel_hi:[1,0]
	s_nop 0
	v_fma_f32 v26, -v31, v31, v30
	v_max_f32_e32 v26, 0, v26
	v_add_f32_e32 v26, 0x3727c5ac, v26
	v_rsq_f32_e32 v30, v26
	s_branch .LBB0_1952

; template <int KSPLIT, class F>
; __device__ __forceinline__ void skinny_gemm(const bf16_t* A, const bf16_t* Bt, int N, int K, const F& f, LAS unsigned char* lds, int bx, int G, int wave) {
;     ...
;     for (int t = bx; t < ntiles; t += G) {
;         const int rg = t % RG, n0 = (t / RG) * 16;
;         const int mt = rg * MTW + (wave % MTW), kq = wave / MTW;
;         const bf16_t* ap = A + (size_t)(MP + 16 * mt + fr) * K + kq * klen + 8 * fq;
;         const bf16_t* bp = Bt + (size_t)(n0 + fr) * K + kq * klen + 8 * fq;
;         f32x4 acc = (f32x4){0.f, 0.f, 0.f, 0.f};
; #pragma unroll 16
;         for (int k = 0; k < klen; k += 32) {
;             const bf16x8 af = *(const bf16x8*)(ap + k), bf = *(const bf16x8*)(bp + k);
;             acc = __builtin_amdgcn_mfma_f32_16x16x32_bf16(bf, af, acc, 0, 0, 0);
;         }
.LBB0_2033:
	s_ashr_i32 s1, s0, 31
	s_lshr_b32 s1, s1, 30
	s_add_i32 s1, s0, s1
	s_ashr_i32 s2, s1, 2
	s_lshl_b32 s1, s2, 4
	s_lshl_b32 s2, s2, 7
	v_subrev_u32_e32 v16, s2, v19
	v_add_u32_e32 v4, 0x4000, v16
	v_mov_b32_e32 v5, v2
	v_lshlrev_b64 v[12:13], 11, v[4:5]
	v_or_b32_e32 v4, s1, v3
	v_ashrrev_i32_e32 v5, 31, v4
	v_lshl_add_u64 v[14:15], v[0:1], 0, v[12:13]
	v_lshlrev_b64 v[4:5], 11, v[4:5]
	v_lshl_add_u64 v[30:31], v[8:9], 0, v[4:5]
	v_readlane_b32 s8, v253, 39
	v_readlane_b32 s9, v253, 40
	s_andn2_b64 vcc, exec, s[8:9]
	v_readlane_b32 s100, v251, 60
	s_mul_i32 s100, s100, 0x3000
	s_add_i32 s100, s100, 0x2000
	v_lshrrev_b32_e32 v202, 2, v219
	v_and_b32_e32 v203, 15, v219
	v_lshrrev_b32_e32 v201, 4, v219
	v_sub_u32_e32 v202, v202, v203
	v_lshlrev_b32_e32 v202, 11, v202
	v_and_b32_e32 v204, 3, v219
	v_xor_b32_e32 v204, v204, v201
	v_sub_u32_e32 v204, v204, v201
	v_lshl_add_u32 v202, v204, 4, v202
	v_lshrrev_b32_e32 v204, 2, v203
	v_xor_b32_e32 v204, v204, v201
	v_lshlrev_b32_e32 v200, 6, v203
	v_lshl_add_u32 v200, v204, 4, v200
	v_add_u32_e32 v200, s100, v200
	v_ashrrev_i32_e32 v203, 31, v202
	v_lshl_add_u64 v[196:197], v[202:203], 0, v[14:15]
	v_lshl_add_u64 v[198:199], v[202:203], 0, v[30:31]
	s_add_i32 m0, s100, 0
	s_nop 0
	global_load_lds_dwordx4 v[196:197], off
	s_add_i32 m0, s100, 1024
	s_nop 0
	global_load_lds_dwordx4 v[198:199], off
	s_add_i32 m0, s100, 1984
	s_nop 0
	global_load_lds_dwordx4 v[196:197], off offset:64
	s_add_i32 m0, s100, 3008
	s_nop 0
	global_load_lds_dwordx4 v[198:199], off offset:64
	s_add_i32 m0, s100, 3968
	s_nop 0
	global_load_lds_dwordx4 v[196:197], off offset:128
	s_add_i32 m0, s100, 4992
	s_nop 0
	global_load_lds_dwordx4 v[198:199], off offset:128
	s_add_i32 m0, s100, 5952
	s_nop 0
	global_load_lds_dwordx4 v[196:197], off offset:192
	s_add_i32 m0, s100, 6976
	s_nop 0
	global_load_lds_dwordx4 v[198:199], off offset:192
	s_add_i32 m0, s100, 7936
	s_nop 0
	global_load_lds_dwordx4 v[196:197], off offset:256
	s_add_i32 m0, s100, 8960
	s_nop 0
	global_load_lds_dwordx4 v[198:199], off offset:256
	s_add_i32 m0, s100, 9920
	s_nop 0
	global_load_lds_dwordx4 v[196:197], off offset:320
	s_add_i32 m0, s100, 10944
	s_nop 0
	global_load_lds_dwordx4 v[198:199], off offset:320
	s_waitcnt vmcnt(10)
	ds_read_b128 v[180:183], v200 offset:0
	ds_read_b128 v[184:187], v200 offset:1024
	s_waitcnt vmcnt(8)
	ds_read_b128 v[188:191], v200 offset:2048
	ds_read_b128 v[192:195], v200 offset:3072
	s_waitcnt lgkmcnt(2)
	v_mfma_f32_16x16x32_bf16 v[4:7], v[184:187], v[180:183], 0
	s_add_i32 m0, s100, -384
	s_nop 0
	global_load_lds_dwordx4 v[196:197], off offset:384
	s_add_i32 m0, s100, 640
	s_nop 0
	global_load_lds_dwordx4 v[198:199], off offset:384
	s_waitcnt vmcnt(8)
	ds_read_b128 v[180:183], v200 offset:4096
	ds_read_b128 v[184:187], v200 offset:5120
	s_waitcnt lgkmcnt(2)
	v_mfma_f32_16x16x32_bf16 v[4:7], v[192:195], v[188:191], v[4:7]
	s_add_i32 m0, s100, 1600
	s_nop 0
	global_load_lds_dwordx4 v[196:197], off offset:448
	s_add_i32 m0, s100, 2624
	s_nop 0
	global_load_lds_dwordx4 v[198:199], off offset:448
	s_waitcnt vmcnt(8)
	ds_read_b128 v[188:191], v200 offset:6144
	ds_read_b128 v[192:195], v200 offset:7168
	s_waitcnt lgkmcnt(2)
	v_mfma_f32_16x16x32_bf16 v[4:7], v[184:187], v[180:183], v[4:7]
	s_waitcnt vmcnt(6)
	ds_read_b128 v[180:183], v200 offset:8192
	ds_read_b128 v[184:187], v200 offset:9216
	s_waitcnt lgkmcnt(2)
	v_mfma_f32_16x16x32_bf16 v[4:7], v[192:195], v[188:191], v[4:7]
	s_waitcnt vmcnt(4)
	ds_read_b128 v[188:191], v200 offset:10240
	ds_read_b128 v[192:195], v200 offset:11264
	s_waitcnt lgkmcnt(2)
	v_mfma_f32_16x16x32_bf16 v[4:7], v[184:187], v[180:183], v[4:7]
	s_waitcnt vmcnt(2)
	ds_read_b128 v[180:183], v200 offset:0
	ds_read_b128 v[184:187], v200 offset:1024
	s_waitcnt lgkmcnt(2)
	v_mfma_f32_16x16x32_bf16 v[4:7], v[192:195], v[188:191], v[4:7]
	s_waitcnt vmcnt(0)
	ds_read_b128 v[188:191], v200 offset:2048
	ds_read_b128 v[192:195], v200 offset:3072
	s_waitcnt lgkmcnt(2)
	v_mfma_f32_16x16x32_bf16 v[4:7], v[184:187], v[180:183], v[4:7]
	s_waitcnt lgkmcnt(0)
	s_barrier
; #define LAS __attribute__((address_space(3)))
; __device__ __forceinline__ u32x2 pk4(f32x4 v) { u32x2 r; r.x = pk2(v.x, v.y); r.y = pk2(v.z, v.w); return r; }
;     __device__ __forceinline__ void sk(int row, int col, f32x4 v, int fq) const {
;         if (fold) { float mu, rs; stats_sk(sts, row, fq, mu, rs); const f32x4 c1v = *(const f32x4*)(c1 + col), c2v = *(const f32x4*)(c2 + col); v = (v - c1v * mu) * rs + c2v; }
;         float d1 = 0.f, d2 = 0.f; f(row, col, v, fq, d1, d2);
;     __device__ __forceinline__ void operator()(int row, int col, f32x4 v, int, float&, float&) const { *(u32x2*)(O + (size_t)row * ldc + col) = pk4(v * s); }
; template <int KSPLIT, class F>
; __device__ __forceinline__ void skinny_gemm(const bf16_t* A, const bf16_t* Bt, int N, int K, const F& f, LAS unsigned char* lds, int bx, int G, int wave) {
;     ...
;             acc = __builtin_amdgcn_mfma_f32_16x16x32_bf16(bf, af, acc, 0, 0, 0);
;         }
;         if (KSPLIT > 1) {
;             __syncthreads();
;             *(LAS f32x4*)(lds + wave * 1024 + lane * 16) = acc;
;             __syncthreads();
;             if (kq == 0) {
; #pragma unroll
;                 for (int q = 1; q < KSPLIT; ++q) acc = acc + *(const LAS f32x4*)(lds + (wave + q * MTW) * 1024 + lane * 16);
;                 f.sk(MP + 16 * mt + fr, n0 + 4 * fq, acc, fq);
	v_mfma_f32_16x16x32_bf16 v[4:7], v[192:195], v[188:191], v[4:7]
	s_nop 7
	ds_write_b128 v20, v[4:7]
	s_waitcnt lgkmcnt(0)
	s_barrier
	s_cbranch_vccnz .LBB0_2032
	ds_read_b128 v[22:25], v20 offset:2048
	v_ashrrev_i32_e32 v17, 31, v16
	v_lshlrev_b64 v[16:17], 9, v[16:17]
	v_lshl_add_u64 v[16:17], v[10:11], 0, v[16:17]
	v_readlane_b32 s8, v252, 19
	s_waitcnt lgkmcnt(0)
	v_pk_add_f32 v[14:15], v[6:7], v[24:25]
	v_pk_add_f32 v[22:23], v[4:5], v[22:23]
	ds_read_b128 v[4:7], v20 offset:4096
	v_readlane_b32 s9, v252, 20
	s_waitcnt lgkmcnt(0)
	v_pk_add_f32 v[14:15], v[14:15], v[6:7]
	v_pk_add_f32 v[22:23], v[22:23], v[4:5]
	ds_read_b128 v[4:7], v20 offset:6144
	v_lshl_add_u64 v[12:13], s[8:9], 0, v[12:13]
	s_waitcnt lgkmcnt(0)
	v_pk_add_f32 v[6:7], v[14:15], v[6:7]
	v_pk_add_f32 v[14:15], v[22:23], v[4:5]
	global_load_dwordx4 v[22:25], v[16:17], off offset:48
	global_load_dwordx4 v[26:29], v[16:17], off offset:32
	global_load_dwordx4 v[30:33], v[16:17], off offset:16
	global_load_dwordx4 v[34:37], v[16:17], off
	global_load_dwordx4 v[38:41], v[16:17], off offset:112
	global_load_dwordx4 v[42:45], v[16:17], off offset:96
	global_load_dwordx4 v[46:49], v[16:17], off offset:80
	global_load_dwordx4 v[50:53], v[16:17], off offset:64
	v_and_b32_e32 v16, 64, v219
	v_xor_b32_e32 v5, 16, v219
	v_add_u32_e32 v16, 64, v16
	v_cmp_lt_i32_e32 vcc, v5, v16
	v_xor_b32_e32 v17, 32, v219
	v_add_u32_e32 v4, s1, v18
	v_cndmask_b32_e32 v5, v219, v5, vcc
	v_cmp_lt_i32_e32 vcc, v17, v16
	v_lshlrev_b32_e32 v5, 2, v5
	s_waitcnt vmcnt(7)
	v_pk_add_f32 v[22:23], v[22:23], v[24:25]
	v_cndmask_b32_e32 v16, v219, v17, vcc
	v_lshlrev_b32_e32 v21, 2, v16
	s_waitcnt vmcnt(4)
	v_pk_add_f32 v[16:17], v[34:35], v[36:37]
	v_pk_add_f32 v[30:31], v[30:31], v[32:33]
	v_pk_add_f32 v[16:17], v[16:17], 0 op_sel_hi:[1,0]
	v_pk_add_f32 v[26:27], v[26:27], v[28:29]
	v_pk_add_f32 v[16:17], v[16:17], v[30:31]
	s_nop 0
	v_pk_add_f32 v[16:17], v[16:17], v[26:27]
	s_nop 0
	v_pk_add_f32 v[16:17], v[16:17], v[22:23]
	s_waitcnt vmcnt(0)
	v_pk_add_f32 v[22:23], v[50:51], v[52:53]
	s_nop 0
	v_pk_add_f32 v[16:17], v[16:17], v[22:23]
	v_pk_add_f32 v[22:23], v[46:47], v[48:49]
	s_nop 0
	v_pk_add_f32 v[16:17], v[16:17], v[22:23]
	v_pk_add_f32 v[22:23], v[42:43], v[44:45]
	s_nop 0
	v_pk_add_f32 v[16:17], v[16:17], v[22:23]
	v_pk_add_f32 v[22:23], v[38:39], v[40:41]
	s_nop 0
	v_pk_add_f32 v[16:17], v[16:17], v[22:23]
	ds_bpermute_b32 v22, v5, v16
	ds_bpermute_b32 v23, v5, v17
	s_waitcnt lgkmcnt(0)
	v_pk_add_f32 v[16:17], v[16:17], v[22:23]
	ds_bpermute_b32 v22, v21, v16
	ds_bpermute_b32 v23, v21, v17
	s_waitcnt lgkmcnt(0)
	v_pk_add_f32 v[16:17], v[16:17], v[22:23]
	s_nop 0
	v_pk_mul_f32 v[16:17], v[16:17], s[82:83] op_sel_hi:[1,0]
	s_nop 0
	v_fma_f32 v5, -v16, v16, v17
	v_max_f32_e32 v5, 0, v5
	v_add_f32_e32 v5, 0x3727c5ac, v5
	v_rsq_f32_e32 v30, v5
	v_ashrrev_i32_e32 v5, 31, v4
	v_lshlrev_b64 v[26:27], 2, v[4:5]
	v_lshl_add_u64 v[22:23], s[42:43], 0, v[26:27]
	global_load_dwordx4 v[22:25], v[22:23], off
	v_lshl_add_u64 v[26:27], s[46:47], 0, v[26:27]
	global_load_dwordx4 v[26:29], v[26:27], off
	v_lshl_add_u64 v[4:5], v[4:5], 1, v[12:13]
	s_waitcnt vmcnt(1)
	v_xor_b32_e32 v25, 0x80000000, v25
	v_xor_b32_e32 v24, 0x80000000, v24
	v_pk_fma_f32 v[6:7], v[24:25], v[16:17], v[6:7] op_sel_hi:[1,0,1]
	v_pk_fma_f32 v[14:15], v[22:23], v[16:17], v[14:15] op_sel_hi:[1,0,1] neg_lo:[1,0,0] neg_hi:[1,0,0]
	s_waitcnt vmcnt(0)
	v_pk_fma_f32 v[6:7], v[6:7], v[30:31], v[28:29] op_sel_hi:[1,0,1]
	v_pk_fma_f32 v[14:15], v[14:15], v[30:31], v[26:27] op_sel_hi:[1,0,1]
	v_pk_mul_f32 v[16:17], v[6:7], s[84:85] op_sel_hi:[1,0]
	v_pk_mul_f32 v[6:7], v[14:15], s[84:85] op_sel_hi:[1,0]
	s_nop 0
	v_cvt_pk_bf16_f32 v6, v6, v7
	v_cvt_pk_bf16_f32 v7, v16, v17
	global_store_dwordx2 v[4:5], v[6:7], off
	s_branch .LBB0_2032

; #define LAS __attribute__((address_space(3)))
; template <int KSPLIT, class F>
; __device__ __forceinline__ void skinny_gemm(const bf16_t* A, const bf16_t* Bt, int N, int K, const F& f, LAS unsigned char* lds, int bx, int G, int wave) {
;     ...
;     for (int t = bx; t < ntiles; t += G) {
;         const int rg = t % RG, n0 = (t / RG) * 16;
;         const int mt = rg * MTW + (wave % MTW), kq = wave / MTW;
;         const bf16_t* ap = A + (size_t)(MP + 16 * mt + fr) * K + kq * klen + 8 * fq;
;         const bf16_t* bp = Bt + (size_t)(n0 + fr) * K + kq * klen + 8 * fq;
;         f32x4 acc = (f32x4){0.f, 0.f, 0.f, 0.f};
; #pragma unroll 16
;         for (int k = 0; k < klen; k += 32) {
;             const bf16x8 af = *(const bf16x8*)(ap + k), bf = *(const bf16x8*)(bp + k);
;             acc = __builtin_amdgcn_mfma_f32_16x16x32_bf16(bf, af, acc, 0, 0, 0);
;         }
;         if (KSPLIT > 1) {
;             __syncthreads();
;             *(LAS f32x4*)(lds + wave * 1024 + lane * 16) = acc;
;             __syncthreads();
;             if (kq == 0) {
; #pragma unroll
;                 for (int q = 1; q < KSPLIT; ++q) acc = acc + *(const LAS f32x4*)(lds + (wave + q * MTW) * 1024 + lane * 16);
;                 f.sk(MP + 16 * mt + fr, n0 + 4 * fq, acc, fq);
.LBB0_2227:
	s_ashr_i32 s0, s4, 31
	s_lshr_b32 s0, s0, 30
	s_add_i32 s0, s4, s0
	s_ashr_i32 s8, s0, 2
	s_lshl_b32 s1, s8, 7
	v_subrev_u32_e32 v12, s1, v23
	v_add_u32_e32 v4, 0x4000, v12
	v_mov_b32_e32 v5, v2
	s_lshl_b32 s0, s8, 4
	v_lshlrev_b64 v[4:5], 11, v[4:5]
	v_lshl_add_u64 v[26:27], v[0:1], 0, v[4:5]
	v_or_b32_e32 v4, s0, v3
	v_ashrrev_i32_e32 v5, 31, v4
	v_lshlrev_b64 v[4:5], 11, v[4:5]
	v_lshl_add_u64 v[28:29], v[8:9], 0, v[4:5]
	s_waitcnt lgkmcnt(0)
	v_readlane_b32 s10, v253, 39
	v_readlane_b32 s11, v253, 40
	s_andn2_b64 vcc, exec, s[10:11]
	v_readlane_b32 s100, v251, 60
	s_mul_i32 s100, s100, 0x3000
	s_add_i32 s100, s100, 0x2000
	v_lshrrev_b32_e32 v202, 2, v219
	v_and_b32_e32 v203, 15, v219
	v_lshrrev_b32_e32 v201, 4, v219
	v_sub_u32_e32 v202, v202, v203
	v_lshlrev_b32_e32 v202, 11, v202
	v_and_b32_e32 v204, 3, v219
	v_xor_b32_e32 v204, v204, v201
	v_sub_u32_e32 v204, v204, v201
	v_lshl_add_u32 v202, v204, 4, v202
	v_lshrrev_b32_e32 v204, 2, v203
	v_xor_b32_e32 v204, v204, v201
	v_lshlrev_b32_e32 v200, 6, v203
	v_lshl_add_u32 v200, v204, 4, v200
	v_add_u32_e32 v200, s100, v200
	v_ashrrev_i32_e32 v203, 31, v202
	v_lshl_add_u64 v[196:197], v[202:203], 0, v[26:27]
	v_lshl_add_u64 v[198:199], v[202:203], 0, v[28:29]
	s_add_i32 m0, s100, 0
	s_nop 0
	global_load_lds_dwordx4 v[196:197], off
	s_add_i32 m0, s100, 1024
	s_nop 0
	global_load_lds_dwordx4 v[198:199], off
	s_add_i32 m0, s100, 1984
	s_nop 0
	global_load_lds_dwordx4 v[196:197], off offset:64
	s_add_i32 m0, s100, 3008
	s_nop 0
	global_load_lds_dwordx4 v[198:199], off offset:64
	s_add_i32 m0, s100, 3968
	s_nop 0
	global_load_lds_dwordx4 v[196:197], off offset:128
	s_add_i32 m0, s100, 4992
	s_nop 0
	global_load_lds_dwordx4 v[198:199], off offset:128
	s_add_i32 m0, s100, 5952
	s_nop 0
	global_load_lds_dwordx4 v[196:197], off offset:192
	s_add_i32 m0, s100, 6976
	s_nop 0
	global_load_lds_dwordx4 v[198:199], off offset:192
	s_add_i32 m0, s100, 7936
	s_nop 0
	global_load_lds_dwordx4 v[196:197], off offset:256
	s_add_i32 m0, s100, 8960
	s_nop 0
	global_load_lds_dwordx4 v[198:199], off offset:256
	s_add_i32 m0, s100, 9920
	s_nop 0
	global_load_lds_dwordx4 v[196:197], off offset:320
	s_add_i32 m0, s100, 10944
	s_nop 0
	global_load_lds_dwordx4 v[198:199], off offset:320
	s_waitcnt vmcnt(10)
	ds_read_b128 v[180:183], v200 offset:0
	ds_read_b128 v[184:187], v200 offset:1024
	s_waitcnt vmcnt(8)
	ds_read_b128 v[188:191], v200 offset:2048
	ds_read_b128 v[192:195], v200 offset:3072
	s_waitcnt lgkmcnt(2)
	v_mfma_f32_16x16x32_bf16 v[4:7], v[184:187], v[180:183], 0
	s_add_i32 m0, s100, -384
	s_nop 0
	global_load_lds_dwordx4 v[196:197], off offset:384
	s_add_i32 m0, s100, 640
	s_nop 0
	global_load_lds_dwordx4 v[198:199], off offset:384
	s_waitcnt vmcnt(8)
	ds_read_b128 v[180:183], v200 offset:4096
	ds_read_b128 v[184:187], v200 offset:5120
	s_waitcnt lgkmcnt(2)
	v_mfma_f32_16x16x32_bf16 v[4:7], v[192:195], v[188:191], v[4:7]
	s_add_i32 m0, s100, 1600
	s_nop 0
	global_load_lds_dwordx4 v[196:197], off offset:448
	s_add_i32 m0, s100, 2624
	s_nop 0
	global_load_lds_dwordx4 v[198:199], off offset:448
	s_waitcnt vmcnt(8)
	ds_read_b128 v[188:191], v200 offset:6144
	ds_read_b128 v[192:195], v200 offset:7168
	s_waitcnt lgkmcnt(2)
	v_mfma_f32_16x16x32_bf16 v[4:7], v[184:187], v[180:183], v[4:7]
	s_waitcnt vmcnt(6)
	ds_read_b128 v[180:183], v200 offset:8192
	ds_read_b128 v[184:187], v200 offset:9216
	s_waitcnt lgkmcnt(2)
	v_mfma_f32_16x16x32_bf16 v[4:7], v[192:195], v[188:191], v[4:7]
	s_waitcnt vmcnt(4)
	ds_read_b128 v[188:191], v200 offset:10240
	ds_read_b128 v[192:195], v200 offset:11264
	s_waitcnt lgkmcnt(2)
	v_mfma_f32_16x16x32_bf16 v[4:7], v[184:187], v[180:183], v[4:7]
	s_waitcnt vmcnt(2)
	ds_read_b128 v[180:183], v200 offset:0
	ds_read_b128 v[184:187], v200 offset:1024
	s_waitcnt lgkmcnt(2)
	v_mfma_f32_16x16x32_bf16 v[4:7], v[192:195], v[188:191], v[4:7]
	s_waitcnt vmcnt(0)
	ds_read_b128 v[188:191], v200 offset:2048
	ds_read_b128 v[192:195], v200 offset:3072
	s_waitcnt lgkmcnt(2)
	v_mfma_f32_16x16x32_bf16 v[4:7], v[184:187], v[180:183], v[4:7]
	s_waitcnt lgkmcnt(0)
	s_barrier
	v_mfma_f32_16x16x32_bf16 v[4:7], v[192:195], v[188:191], v[4:7]
	s_nop 7
	ds_write_b128 v25, v[4:7]
	s_waitcnt lgkmcnt(0)
	s_barrier
	s_cbranch_vccnz .LBB0_2226
; #define LAS __attribute__((address_space(3)))
; __device__ __forceinline__ u32x2 pk4(f32x4 v) { u32x2 r; r.x = pk2(v.x, v.y); r.y = pk2(v.z, v.w); return r; }
;     __device__ __forceinline__ void sk(int row, int col, f32x4 v, int fq) const {
;         float mu = 0.f, rs = 1.f; if (ln) stats_sk(sts_p, row, fq, mu, rs);
;         const u32x2 raw = *(const u32x2*)(src + (size_t)row * DM + col);
;         f32x4 x = (f32x4){bflo(raw.x), bfhi(raw.x), bflo(raw.y), bfhi(raw.y)};
;         if (ln) x = (x - mu) * rs * *(const f32x4*)(g + col) + *(const f32x4*)(b + col);
;         const u32x2 pz = pk4(x * ALPHA + v);
;         *(u32x2*)(dst + (size_t)row * DM + col) = pz;
;         const float z0 = bflo(pz.x), z1 = bfhi(pz.x), z2 = bflo(pz.y), z3 = bfhi(pz.y);
;         float s1 = (z0 + z1) + (z2 + z3), s2 = (z0 * z0 + z1 * z1) + (z2 * z2 + z3 * z3);
;         s1 += __shfl_xor(s1, 16); s2 += __shfl_xor(s2, 16); s1 += __shfl_xor(s1, 32); s2 += __shfl_xor(s2, 32);
;         if (fq == 0) { float* p = sts_n + (size_t)(row - MP) * 128 + (col >> 4) * 2; p[0] = s1; p[1] = s2; }
; template <int KSPLIT, class F>
; __device__ __forceinline__ void skinny_gemm(const bf16_t* A, const bf16_t* Bt, int N, int K, const F& f, LAS unsigned char* lds, int bx, int G, int wave) {
;     ...
;             if (kq == 0) {
; #pragma unroll
;                 for (int q = 1; q < KSPLIT; ++q) acc = acc + *(const LAS f32x4*)(lds + (wave + q * MTW) * 1024 + lane * 16);
;                 f.sk(MP + 16 * mt + fr, n0 + 4 * fq, acc, fq);
	ds_read_b128 v[14:17], v25 offset:2048
	v_ashrrev_i32_e32 v13, 31, v12
	v_lshlrev_b64 v[12:13], 9, v[12:13]
	v_lshl_add_u64 v[20:21], v[10:11], 0, v[12:13]
	s_waitcnt lgkmcnt(0)
	v_pk_add_f32 v[16:17], v[6:7], v[16:17]
	v_pk_add_f32 v[14:15], v[4:5], v[14:15]
	ds_read_b128 v[4:7], v25 offset:4096
	s_waitcnt lgkmcnt(0)
	v_pk_add_f32 v[6:7], v[16:17], v[6:7]
	v_pk_add_f32 v[18:19], v[14:15], v[4:5]
	ds_read_b128 v[14:17], v25 offset:6144
	s_waitcnt lgkmcnt(0)
	v_pk_add_f32 v[4:5], v[6:7], v[16:17]
	v_pk_add_f32 v[6:7], v[18:19], v[14:15]
	global_load_dwordx4 v[16:19], v[20:21], off offset:48
	global_load_dwordx4 v[28:31], v[20:21], off offset:32
	global_load_dwordx4 v[32:35], v[20:21], off offset:16
	global_load_dwordx4 v[36:39], v[20:21], off
	global_load_dwordx4 v[40:43], v[20:21], off offset:112
	global_load_dwordx4 v[44:47], v[20:21], off offset:96
	global_load_dwordx4 v[48:51], v[20:21], off offset:80
	global_load_dwordx4 v[52:55], v[20:21], off offset:64
	v_and_b32_e32 v20, 64, v219
	v_xor_b32_e32 v15, 16, v219
	v_add_u32_e32 v20, 64, v20
	v_cmp_lt_i32_e32 vcc, v15, v20
	v_add_u32_e32 v14, s0, v22
	s_lshl_b32 s0, s8, 17
	v_cndmask_b32_e32 v15, v219, v15, vcc
	v_lshlrev_b32_e32 v27, 2, v15
	v_xor_b32_e32 v15, 32, v219
	v_cmp_lt_i32_e32 vcc, v15, v20
	s_waitcnt vmcnt(7)
	v_pk_add_f32 v[16:17], v[16:17], v[18:19]
	s_waitcnt vmcnt(6)
	v_pk_add_f32 v[28:29], v[28:29], v[30:31]
	s_waitcnt vmcnt(5)
	v_pk_add_f32 v[32:33], v[32:33], v[34:35]
	s_waitcnt vmcnt(4)
	v_pk_add_f32 v[20:21], v[36:37], v[38:39]
	v_cndmask_b32_e32 v15, v219, v15, vcc
	v_pk_add_f32 v[20:21], v[20:21], 0 op_sel_hi:[1,0]
	v_lshlrev_b32_e32 v26, 2, v15
	v_pk_add_f32 v[20:21], v[20:21], v[32:33]
	s_waitcnt vmcnt(0)
	v_pk_add_f32 v[18:19], v[52:53], v[54:55]
	v_pk_add_f32 v[20:21], v[20:21], v[28:29]
	s_nop 0
	v_pk_add_f32 v[16:17], v[20:21], v[16:17]
	s_nop 0
	v_pk_add_f32 v[16:17], v[16:17], v[18:19]
	v_pk_add_f32 v[18:19], v[48:49], v[50:51]
	s_nop 0
	v_pk_add_f32 v[16:17], v[16:17], v[18:19]
	v_pk_add_f32 v[18:19], v[44:45], v[46:47]
	s_nop 0
	v_pk_add_f32 v[16:17], v[16:17], v[18:19]
	v_pk_add_f32 v[18:19], v[40:41], v[42:43]
	s_nop 0
	v_pk_add_f32 v[16:17], v[16:17], v[18:19]
	ds_bpermute_b32 v18, v27, v16
	ds_bpermute_b32 v19, v27, v17
	s_waitcnt lgkmcnt(0)
	v_pk_add_f32 v[16:17], v[16:17], v[18:19]
	ds_bpermute_b32 v18, v26, v16
	ds_bpermute_b32 v19, v26, v17
	s_waitcnt lgkmcnt(0)
	v_pk_add_f32 v[16:17], v[16:17], v[18:19]
	s_nop 0
	v_pk_mul_f32 v[18:19], v[16:17], s[82:83] op_sel_hi:[1,0]
	v_subrev_u32_e32 v16, s0, v24
	v_fma_f32 v15, -v18, v18, v19
	v_max_f32_e32 v15, 0, v15
	v_add_f32_e32 v15, 0x3727c5ac, v15
	v_mov_b32_e32 v17, v2
	v_rsq_f32_e32 v20, v15
	v_lshl_add_u64 v[16:17], v[16:17], 1, s[70:71]
	v_ashrrev_i32_e32 v15, 31, v14
	v_lshl_add_u64 v[16:17], v[14:15], 1, v[16:17]
	global_load_dwordx2 v[28:29], v[16:17], off
	v_lshlrev_b64 v[14:15], 2, v[14:15]
	s_waitcnt vmcnt(0)
	v_lshlrev_b32_e32 v19, 16, v28
	v_and_b32_e32 v21, 0xffff0000, v28
	v_lshlrev_b32_e32 v30, 16, v29
	v_and_b32_e32 v31, 0xffff0000, v29
	v_sub_f32_e32 v29, v21, v18
	v_sub_f32_e32 v28, v19, v18
	v_sub_f32_e32 v19, v31, v18
	v_sub_f32_e32 v18, v30, v18
	v_pk_mul_f32 v[18:19], v[20:21], v[18:19] op_sel_hi:[0,1]
	v_pk_mul_f32 v[20:21], v[20:21], v[28:29] op_sel_hi:[0,1]
	v_lshl_add_u64 v[28:29], s[46:47], 0, v[14:15]
	v_lshl_add_u64 v[14:15], s[48:49], 0, v[14:15]
	global_load_dwordx4 v[28:31], v[28:29], off
	s_nop 0
	global_load_dwordx4 v[32:35], v[14:15], off
	s_waitcnt vmcnt(0)
	v_pk_fma_f32 v[14:15], v[28:29], v[20:21], v[32:33]
	v_pk_fma_f32 v[18:19], v[30:31], v[18:19], v[34:35]
	v_pk_fma_f32 v[6:7], v[14:15], s[72:73], v[6:7] op_sel_hi:[1,0,1]
	v_pk_fma_f32 v[4:5], v[18:19], s[72:73], v[4:5] op_sel_hi:[1,0,1]
	v_cvt_pk_bf16_f32 v6, v6, v7
	v_cvt_pk_bf16_f32 v7, v4, v5
	global_store_dwordx2 v[16:17], v[6:7], off
	v_lshlrev_b32_e32 v4, 16, v6
	v_and_b32_e32 v6, 0xffff0000, v6
	v_lshlrev_b32_e32 v14, 16, v7
	v_and_b32_e32 v16, 0xffff0000, v7
	v_mul_f32_e32 v5, v4, v4
	v_mul_f32_e32 v7, v6, v6
	v_mul_f32_e32 v15, v14, v14
	v_mul_f32_e32 v17, v16, v16
	v_pk_add_f32 v[4:5], v[4:5], v[6:7]
	v_pk_add_f32 v[6:7], v[14:15], v[16:17]
	s_nop 0
	v_pk_add_f32 v[4:5], v[4:5], v[6:7]
	ds_bpermute_b32 v6, v27, v4
	ds_bpermute_b32 v7, v27, v5
	s_waitcnt lgkmcnt(0)
	v_pk_add_f32 v[4:5], v[4:5], v[6:7]
	ds_bpermute_b32 v6, v26, v4
	ds_bpermute_b32 v7, v26, v5
	s_and_saveexec_b64 s[0:1], s[38:39]
	s_cbranch_execz .LBB0_2225
	s_lshl_b32 s8, s8, 1
	v_lshl_add_u64 v[12:13], s[40:41], 0, v[12:13]
	s_ashr_i32 s9, s8, 31
	v_lshl_add_u64 v[12:13], s[8:9], 2, v[12:13]
	s_waitcnt lgkmcnt(0)
	v_pk_add_f32 v[4:5], v[4:5], v[6:7]
	global_store_dwordx2 v[12:13], v[4:5], off
	s_branch .LBB0_2225

; template <int KSPLIT, class F>
; __device__ __forceinline__ void skinny_gemm(const bf16_t* A, const bf16_t* Bt, int N, int K, const F& f, LAS unsigned char* lds, int bx, int G, int wave) {
;     ...
; #pragma unroll 16
;         for (int k = 0; k < klen; k += 32) {
;             const bf16x8 af = *(const bf16x8*)(ap + k), bf = *(const bf16x8*)(bp + k);
;             acc = __builtin_amdgcn_mfma_f32_16x16x32_bf16(bf, af, acc, 0, 0, 0);
;         }
.LBB0_2306:
	v_readlane_b32 s100, v251, 60
	s_mul_i32 s100, s100, 0x3000
	s_add_i32 s100, s100, 0x2000
	v_lshrrev_b32_e32 v202, 2, v219
	v_and_b32_e32 v203, 15, v219
	v_lshrrev_b32_e32 v201, 4, v219
	v_sub_u32_e32 v202, v202, v203
	v_lshlrev_b32_e32 v202, 11, v202
	v_and_b32_e32 v204, 3, v219
	v_xor_b32_e32 v204, v204, v201
	v_sub_u32_e32 v204, v204, v201
	v_lshl_add_u32 v202, v204, 4, v202
	v_lshrrev_b32_e32 v204, 2, v203
	v_xor_b32_e32 v204, v204, v201
	v_lshlrev_b32_e32 v200, 6, v203
	v_lshl_add_u32 v200, v204, 4, v200
	v_add_u32_e32 v200, s100, v200
	v_ashrrev_i32_e32 v203, 31, v202
	v_lshl_add_u64 v[196:197], v[202:203], 0, v[18:19]
	v_lshl_add_u64 v[198:199], v[202:203], 0, v[16:17]
	s_add_i32 m0, s100, 512
	s_nop 0
	global_load_lds_dwordx4 v[196:197], off offset:-512
	s_add_i32 m0, s100, 1536
	s_nop 0
	global_load_lds_dwordx4 v[198:199], off offset:-512
	s_add_i32 m0, s100, 2496
	s_nop 0
	global_load_lds_dwordx4 v[196:197], off offset:-448
	s_add_i32 m0, s100, 3520
	s_nop 0
	global_load_lds_dwordx4 v[198:199], off offset:-448
	s_add_i32 m0, s100, 4480
	s_nop 0
	global_load_lds_dwordx4 v[196:197], off offset:-384
	s_add_i32 m0, s100, 5504
	s_nop 0
	global_load_lds_dwordx4 v[198:199], off offset:-384
	s_add_i32 m0, s100, 6464
	s_nop 0
	global_load_lds_dwordx4 v[196:197], off offset:-320
	s_add_i32 m0, s100, 7488
	s_nop 0
	global_load_lds_dwordx4 v[198:199], off offset:-320
	s_add_i32 m0, s100, 8448
	s_nop 0
	global_load_lds_dwordx4 v[196:197], off offset:-256
	s_add_i32 m0, s100, 9472
	s_nop 0
	global_load_lds_dwordx4 v[198:199], off offset:-256
	s_add_i32 m0, s100, 10432
	s_nop 0
	global_load_lds_dwordx4 v[196:197], off offset:-192
	s_add_i32 m0, s100, 11456
	s_nop 0
	global_load_lds_dwordx4 v[198:199], off offset:-192
	s_waitcnt vmcnt(10)
	ds_read_b128 v[180:183], v200 offset:0
	ds_read_b128 v[184:187], v200 offset:1024
	s_waitcnt vmcnt(8)
	ds_read_b128 v[188:191], v200 offset:2048
	ds_read_b128 v[192:195], v200 offset:3072
	s_waitcnt lgkmcnt(2)
	v_mfma_f32_16x16x32_bf16 v[4:7], v[184:187], v[180:183], v[4:7]
	s_add_i32 m0, s100, 128
	s_nop 0
	global_load_lds_dwordx4 v[196:197], off offset:-128
	s_add_i32 m0, s100, 1152
	s_nop 0
	global_load_lds_dwordx4 v[198:199], off offset:-128
	s_waitcnt vmcnt(8)
	ds_read_b128 v[180:183], v200 offset:4096
	ds_read_b128 v[184:187], v200 offset:5120
	s_waitcnt lgkmcnt(2)
	v_mfma_f32_16x16x32_bf16 v[4:7], v[192:195], v[188:191], v[4:7]
	s_add_i32 m0, s100, 2112
	s_nop 0
	global_load_lds_dwordx4 v[196:197], off offset:-64
	s_add_i32 m0, s100, 3136
	s_nop 0
	global_load_lds_dwordx4 v[198:199], off offset:-64
	s_waitcnt vmcnt(8)
	ds_read_b128 v[188:191], v200 offset:6144
	ds_read_b128 v[192:195], v200 offset:7168
	s_waitcnt lgkmcnt(2)
	v_mfma_f32_16x16x32_bf16 v[4:7], v[184:187], v[180:183], v[4:7]
	s_add_i32 m0, s100, 4096
	s_nop 0
	global_load_lds_dwordx4 v[196:197], off
	s_add_i32 m0, s100, 5120
	s_nop 0
	global_load_lds_dwordx4 v[198:199], off
	s_waitcnt vmcnt(8)
	ds_read_b128 v[180:183], v200 offset:8192
	ds_read_b128 v[184:187], v200 offset:9216
	s_waitcnt lgkmcnt(2)
	v_mfma_f32_16x16x32_bf16 v[4:7], v[192:195], v[188:191], v[4:7]
	s_add_i32 m0, s100, 6080
	s_nop 0
	global_load_lds_dwordx4 v[196:197], off offset:64
	s_add_i32 m0, s100, 7104
	s_nop 0
	global_load_lds_dwordx4 v[198:199], off offset:64
	s_waitcnt vmcnt(8)
	ds_read_b128 v[188:191], v200 offset:10240
	ds_read_b128 v[192:195], v200 offset:11264
	s_waitcnt lgkmcnt(2)
	v_mfma_f32_16x16x32_bf16 v[4:7], v[184:187], v[180:183], v[4:7]
	s_add_i32 m0, s100, 8064
	s_nop 0
	global_load_lds_dwordx4 v[196:197], off offset:128
	s_add_i32 m0, s100, 9088
	s_nop 0
	global_load_lds_dwordx4 v[198:199], off offset:128
	s_waitcnt vmcnt(8)
	ds_read_b128 v[180:183], v200 offset:0
	ds_read_b128 v[184:187], v200 offset:1024
	s_waitcnt lgkmcnt(2)
	v_mfma_f32_16x16x32_bf16 v[4:7], v[192:195], v[188:191], v[4:7]
	s_add_i32 m0, s100, 10048
	s_nop 0
	global_load_lds_dwordx4 v[196:197], off offset:192
	s_add_i32 m0, s100, 11072
	s_nop 0
	global_load_lds_dwordx4 v[198:199], off offset:192
	s_waitcnt vmcnt(8)
	ds_read_b128 v[188:191], v200 offset:2048
	ds_read_b128 v[192:195], v200 offset:3072
	s_waitcnt lgkmcnt(2)
	v_mfma_f32_16x16x32_bf16 v[4:7], v[184:187], v[180:183], v[4:7]
	s_add_i32 m0, s100, -256
	s_nop 0
	global_load_lds_dwordx4 v[196:197], off offset:256
	s_add_i32 m0, s100, 768
	s_nop 0
	global_load_lds_dwordx4 v[198:199], off offset:256
	s_waitcnt vmcnt(8)
	ds_read_b128 v[180:183], v200 offset:4096
	ds_read_b128 v[184:187], v200 offset:5120
	s_waitcnt lgkmcnt(2)
	v_mfma_f32_16x16x32_bf16 v[4:7], v[192:195], v[188:191], v[4:7]
	s_add_i32 m0, s100, 1728
	s_nop 0
	global_load_lds_dwordx4 v[196:197], off offset:320
	s_add_i32 m0, s100, 2752
	s_nop 0
	global_load_lds_dwordx4 v[198:199], off offset:320
	s_waitcnt vmcnt(8)
	ds_read_b128 v[188:191], v200 offset:6144
	ds_read_b128 v[192:195], v200 offset:7168
	s_waitcnt lgkmcnt(2)
	v_mfma_f32_16x16x32_bf16 v[4:7], v[184:187], v[180:183], v[4:7]
	s_add_i32 m0, s100, 3712
	s_nop 0
	global_load_lds_dwordx4 v[196:197], off offset:384
	s_add_i32 m0, s100, 4736
	s_nop 0
	global_load_lds_dwordx4 v[198:199], off offset:384
	s_waitcnt vmcnt(8)
	ds_read_b128 v[180:183], v200 offset:8192
	ds_read_b128 v[184:187], v200 offset:9216
	s_waitcnt lgkmcnt(2)
	v_mfma_f32_16x16x32_bf16 v[4:7], v[192:195], v[188:191], v[4:7]
	s_add_i32 m0, s100, 5696
	s_nop 0
	global_load_lds_dwordx4 v[196:197], off offset:448
	s_add_i32 m0, s100, 6720
	s_nop 0
	global_load_lds_dwordx4 v[198:199], off offset:448
	s_waitcnt vmcnt(8)
	ds_read_b128 v[188:191], v200 offset:10240
	ds_read_b128 v[192:195], v200 offset:11264
	s_waitcnt lgkmcnt(2)
; template <int KSPLIT, class F>
; __device__ __forceinline__ void skinny_gemm(const bf16_t* A, const bf16_t* Bt, int N, int K, const F& f, LAS unsigned char* lds, int bx, int G, int wave) {
;     ...
;         for (int k = 0; k < klen; k += 32) {
;             const bf16x8 af = *(const bf16x8*)(ap + k), bf = *(const bf16x8*)(bp + k);
;             acc = __builtin_amdgcn_mfma_f32_16x16x32_bf16(bf, af, acc, 0, 0, 0);
;         }
	v_mfma_f32_16x16x32_bf16 v[4:7], v[184:187], v[180:183], v[4:7]
	s_add_i32 m0, s100, 7680
	s_nop 0
	global_load_lds_dwordx4 v[196:197], off offset:512
	s_add_i32 m0, s100, 8704
	s_nop 0
	global_load_lds_dwordx4 v[198:199], off offset:512
	s_waitcnt vmcnt(8)
	ds_read_b128 v[180:183], v200 offset:0
	ds_read_b128 v[184:187], v200 offset:1024
	s_waitcnt lgkmcnt(2)
	v_mfma_f32_16x16x32_bf16 v[4:7], v[192:195], v[188:191], v[4:7]
	s_add_i32 m0, s100, 9664
	s_nop 0
	global_load_lds_dwordx4 v[196:197], off offset:576
	s_add_i32 m0, s100, 10688
	s_nop 0
	global_load_lds_dwordx4 v[198:199], off offset:576
	s_waitcnt vmcnt(8)
	ds_read_b128 v[188:191], v200 offset:2048
	ds_read_b128 v[192:195], v200 offset:3072
	s_waitcnt lgkmcnt(2)
	v_mfma_f32_16x16x32_bf16 v[4:7], v[184:187], v[180:183], v[4:7]
	s_add_i32 m0, s100, -640
	s_nop 0
	global_load_lds_dwordx4 v[196:197], off offset:640
	s_add_i32 m0, s100, 384
	s_nop 0
	global_load_lds_dwordx4 v[198:199], off offset:640
	s_waitcnt vmcnt(8)
	ds_read_b128 v[180:183], v200 offset:4096
	ds_read_b128 v[184:187], v200 offset:5120
	s_waitcnt lgkmcnt(2)
	v_mfma_f32_16x16x32_bf16 v[4:7], v[192:195], v[188:191], v[4:7]
	s_add_i32 m0, s100, 1344
	s_nop 0
	global_load_lds_dwordx4 v[196:197], off offset:704
	s_add_i32 m0, s100, 2368
	s_nop 0
	global_load_lds_dwordx4 v[198:199], off offset:704
	s_waitcnt vmcnt(8)
	ds_read_b128 v[188:191], v200 offset:6144
	ds_read_b128 v[192:195], v200 offset:7168
	s_waitcnt lgkmcnt(2)
	v_mfma_f32_16x16x32_bf16 v[4:7], v[184:187], v[180:183], v[4:7]
	s_add_i32 m0, s100, 3328
	s_nop 0
	global_load_lds_dwordx4 v[196:197], off offset:768
	s_add_i32 m0, s100, 4352
	s_nop 0
	global_load_lds_dwordx4 v[198:199], off offset:768
	s_waitcnt vmcnt(8)
	ds_read_b128 v[180:183], v200 offset:8192
	ds_read_b128 v[184:187], v200 offset:9216
	s_waitcnt lgkmcnt(2)
	v_mfma_f32_16x16x32_bf16 v[4:7], v[192:195], v[188:191], v[4:7]
	s_add_i32 m0, s100, 5312
	s_nop 0
	global_load_lds_dwordx4 v[196:197], off offset:832
	s_add_i32 m0, s100, 6336
	s_nop 0
	global_load_lds_dwordx4 v[198:199], off offset:832
	s_waitcnt vmcnt(8)
	ds_read_b128 v[188:191], v200 offset:10240
	ds_read_b128 v[192:195], v200 offset:11264
	s_waitcnt lgkmcnt(2)
	v_mfma_f32_16x16x32_bf16 v[4:7], v[184:187], v[180:183], v[4:7]
	s_add_i32 m0, s100, 7296
	s_nop 0
	global_load_lds_dwordx4 v[196:197], off offset:896
	s_add_i32 m0, s100, 8320
	s_nop 0
	global_load_lds_dwordx4 v[198:199], off offset:896
	s_waitcnt vmcnt(8)
	ds_read_b128 v[180:183], v200 offset:0
	ds_read_b128 v[184:187], v200 offset:1024
	s_waitcnt lgkmcnt(2)
	v_mfma_f32_16x16x32_bf16 v[4:7], v[192:195], v[188:191], v[4:7]
	s_add_i32 m0, s100, 9280
	s_nop 0
	global_load_lds_dwordx4 v[196:197], off offset:960
	s_add_i32 m0, s100, 10304
	s_nop 0
	global_load_lds_dwordx4 v[198:199], off offset:960
	s_waitcnt vmcnt(8)
	ds_read_b128 v[188:191], v200 offset:2048
	ds_read_b128 v[192:195], v200 offset:3072
	s_waitcnt lgkmcnt(2)
	v_mfma_f32_16x16x32_bf16 v[4:7], v[184:187], v[180:183], v[4:7]
	s_add_i32 m0, s100, -1024
	s_nop 0
	global_load_lds_dwordx4 v[196:197], off offset:1024
	s_add_i32 m0, s100, 0
	s_nop 0
	global_load_lds_dwordx4 v[198:199], off offset:1024
	s_waitcnt vmcnt(8)
	ds_read_b128 v[180:183], v200 offset:4096
	ds_read_b128 v[184:187], v200 offset:5120
	s_waitcnt lgkmcnt(2)
	v_mfma_f32_16x16x32_bf16 v[4:7], v[192:195], v[188:191], v[4:7]
	s_add_i32 m0, s100, 960
	s_nop 0
	global_load_lds_dwordx4 v[196:197], off offset:1088
	s_add_i32 m0, s100, 1984
	s_nop 0
	global_load_lds_dwordx4 v[198:199], off offset:1088
	s_waitcnt vmcnt(8)
	ds_read_b128 v[188:191], v200 offset:6144
	ds_read_b128 v[192:195], v200 offset:7168
	s_waitcnt lgkmcnt(2)
	v_mfma_f32_16x16x32_bf16 v[4:7], v[184:187], v[180:183], v[4:7]
	s_add_i32 m0, s100, 2944
	s_nop 0
	global_load_lds_dwordx4 v[196:197], off offset:1152
	s_add_i32 m0, s100, 3968
	s_nop 0
	global_load_lds_dwordx4 v[198:199], off offset:1152
	s_waitcnt vmcnt(8)
	ds_read_b128 v[180:183], v200 offset:8192
	ds_read_b128 v[184:187], v200 offset:9216
	s_waitcnt lgkmcnt(2)
	v_mfma_f32_16x16x32_bf16 v[4:7], v[192:195], v[188:191], v[4:7]
	s_add_i32 m0, s100, 4928
	s_nop 0
	global_load_lds_dwordx4 v[196:197], off offset:1216
	s_add_i32 m0, s100, 5952
	s_nop 0
	global_load_lds_dwordx4 v[198:199], off offset:1216
	s_waitcnt vmcnt(8)
	ds_read_b128 v[188:191], v200 offset:10240
	ds_read_b128 v[192:195], v200 offset:11264
	s_waitcnt lgkmcnt(2)
	v_mfma_f32_16x16x32_bf16 v[4:7], v[184:187], v[180:183], v[4:7]
	s_add_i32 m0, s100, 6912
	s_nop 0
	global_load_lds_dwordx4 v[196:197], off offset:1280
	s_add_i32 m0, s100, 7936
	s_nop 0
	global_load_lds_dwordx4 v[198:199], off offset:1280
	s_waitcnt vmcnt(8)
	ds_read_b128 v[180:183], v200 offset:0
	ds_read_b128 v[184:187], v200 offset:1024
	s_waitcnt lgkmcnt(2)
; __device__ __forceinline__ u32x2 pk4(f32x4 v) { u32x2 r; r.x = pk2(v.x, v.y); r.y = pk2(v.z, v.w); return r; }
;     __device__ __forceinline__ void operator()(int row, int col, f32x4 v, int, float&, float&) const { *(u32x2*)(O + (size_t)row * ldc + col) = pk4(v * s); }
; __device__ __forceinline__ void stats_sk(const float* sts, int row, int fq, float& mu, float& rs) {
;     const f32x4* p = (const f32x4*)(sts + (size_t)(row - MP) * 128 + fq * 32);
;     float s1 = 0.f, s2 = 0.f;
; #pragma unroll
;     for (int i = 0; i < 8; ++i) { const f32x4 a = p[i]; s1 += a.x + a.z; s2 += a.y + a.w; }
;     s1 += __shfl_xor(s1, 16); s2 += __shfl_xor(s2, 16); s1 += __shfl_xor(s1, 32); s2 += __shfl_xor(s2, 32);
;     mu = s1 * (1.f / DM); rs = __builtin_amdgcn_rsqf(fmaxf(s2 * (1.f / DM) - mu * mu, 0.f) + LN_EPS);
; }
;     __device__ __forceinline__ void sk(int row, int col, f32x4 v, int fq) const {
;         if (fold) { float mu, rs; stats_sk(sts, row, fq, mu, rs); const f32x4 c1v = *(const f32x4*)(c1 + col), c2v = *(const f32x4*)(c2 + col); v = (v - c1v * mu) * rs + c2v; }
;         float d1 = 0.f, d2 = 0.f; f(row, col, v, fq, d1, d2);
;     __device__ __forceinline__ void operator()(int row, int col, f32x4 v, int, float&, float&) const {
;         f32x4 r; r.x = fmaxf(v.x, 0.f); r.y = fmaxf(v.y, 0.f); r.z = fmaxf(v.z, 0.f); r.w = fmaxf(v.w, 0.f);
;         *(u32x2*)(O + (size_t)row * FF + col) = pk4(r * r);
;     }
; template <int KSPLIT, class F>
; __device__ __forceinline__ void skinny_gemm(const bf16_t* A, const bf16_t* Bt, int N, int K, const F& f, LAS unsigned char* lds, int bx, int G, int wave) {
;     ...
;         for (int k = 0; k < klen; k += 32) {
;             const bf16x8 af = *(const bf16x8*)(ap + k), bf = *(const bf16x8*)(bp + k);
;             acc = __builtin_amdgcn_mfma_f32_16x16x32_bf16(bf, af, acc, 0, 0, 0);
;         }
	v_mfma_f32_16x16x32_bf16 v[4:7], v[192:195], v[188:191], v[4:7]
	s_add_i32 m0, s100, 8896
	s_nop 0
	global_load_lds_dwordx4 v[196:197], off offset:1344
	s_add_i32 m0, s100, 9920
	s_nop 0
	global_load_lds_dwordx4 v[198:199], off offset:1344
	s_waitcnt vmcnt(8)
	ds_read_b128 v[188:191], v200 offset:2048
	ds_read_b128 v[192:195], v200 offset:3072
	s_waitcnt lgkmcnt(2)
	v_mfma_f32_16x16x32_bf16 v[4:7], v[184:187], v[180:183], v[4:7]
	s_add_i32 m0, s100, -1408
	s_nop 0
	global_load_lds_dwordx4 v[196:197], off offset:1408
	s_add_i32 m0, s100, -384
	s_nop 0
	global_load_lds_dwordx4 v[198:199], off offset:1408
	s_waitcnt vmcnt(8)
	ds_read_b128 v[180:183], v200 offset:4096
	ds_read_b128 v[184:187], v200 offset:5120
	s_waitcnt lgkmcnt(2)
	v_mfma_f32_16x16x32_bf16 v[4:7], v[192:195], v[188:191], v[4:7]
	s_add_i32 m0, s100, 576
	s_nop 0
	global_load_lds_dwordx4 v[196:197], off offset:1472
	s_add_i32 m0, s100, 1600
	s_nop 0
	global_load_lds_dwordx4 v[198:199], off offset:1472
	s_waitcnt vmcnt(8)
	ds_read_b128 v[188:191], v200 offset:6144
	ds_read_b128 v[192:195], v200 offset:7168
	s_waitcnt lgkmcnt(2)
	v_mfma_f32_16x16x32_bf16 v[4:7], v[184:187], v[180:183], v[4:7]
	s_waitcnt vmcnt(6)
	ds_read_b128 v[180:183], v200 offset:8192
	ds_read_b128 v[184:187], v200 offset:9216
	s_waitcnt lgkmcnt(2)
	v_mfma_f32_16x16x32_bf16 v[4:7], v[192:195], v[188:191], v[4:7]
	s_waitcnt vmcnt(4)
	ds_read_b128 v[188:191], v200 offset:10240
	ds_read_b128 v[192:195], v200 offset:11264
	s_waitcnt lgkmcnt(2)
	v_mfma_f32_16x16x32_bf16 v[4:7], v[184:187], v[180:183], v[4:7]
	s_waitcnt vmcnt(2)
	ds_read_b128 v[180:183], v200 offset:0
	ds_read_b128 v[184:187], v200 offset:1024
	s_waitcnt lgkmcnt(2)
	v_mfma_f32_16x16x32_bf16 v[4:7], v[192:195], v[188:191], v[4:7]
	s_waitcnt vmcnt(0)
	ds_read_b128 v[188:191], v200 offset:2048
	ds_read_b128 v[192:195], v200 offset:3072
	s_waitcnt lgkmcnt(2)
	v_mfma_f32_16x16x32_bf16 v[4:7], v[184:187], v[180:183], v[4:7]
	s_waitcnt lgkmcnt(0)
	v_mfma_f32_16x16x32_bf16 v[4:7], v[192:195], v[188:191], v[4:7]
	s_nop 0
	global_load_dwordx4 v[16:19], v[0:1], off offset:48
	global_load_dwordx4 v[22:25], v[0:1], off offset:32
	global_load_dwordx4 v[26:29], v[0:1], off offset:16
	global_load_dwordx4 v[30:33], v[0:1], off
	global_load_dwordx4 v[34:37], v[0:1], off offset:112
	global_load_dwordx4 v[38:41], v[0:1], off offset:96
	global_load_dwordx4 v[42:45], v[0:1], off offset:80
	global_load_dwordx4 v[46:49], v[0:1], off offset:64
	v_lshl_add_u32 v50, s0, 4, v3
	v_ashrrev_i32_e32 v51, 31, v50
	s_add_i32 s0, s0, s26
	v_readlane_b32 s1, v254, 54
	s_cmpk_gt_i32 s0, 0xff
	s_waitcnt vmcnt(7)
	v_pk_add_f32 v[16:17], v[16:17], v[18:19]
	s_waitcnt vmcnt(6)
	v_pk_add_f32 v[22:23], v[22:23], v[24:25]
	s_waitcnt vmcnt(5)
	v_pk_add_f32 v[26:27], v[26:27], v[28:29]
	s_waitcnt vmcnt(4)
	v_pk_add_f32 v[30:31], v[30:31], v[32:33]
	v_add_u32_e32 v12, s1, v12
	v_pk_add_f32 v[30:31], v[30:31], 0 op_sel_hi:[1,0]
	s_waitcnt vmcnt(0)
	v_pk_add_f32 v[18:19], v[46:47], v[48:49]
	v_pk_add_f32 v[26:27], v[30:31], v[26:27]
	s_nop 0
	v_pk_add_f32 v[22:23], v[26:27], v[22:23]
	s_nop 0
	v_pk_add_f32 v[16:17], v[22:23], v[16:17]
	v_lshlrev_b64 v[22:23], 2, v[50:51]
	v_pk_add_f32 v[16:17], v[16:17], v[18:19]
	v_pk_add_f32 v[18:19], v[42:43], v[44:45]
	s_nop 0
	v_pk_add_f32 v[16:17], v[16:17], v[18:19]
	v_pk_add_f32 v[18:19], v[38:39], v[40:41]
	s_nop 0
	v_pk_add_f32 v[16:17], v[16:17], v[18:19]
	v_pk_add_f32 v[18:19], v[34:35], v[36:37]
	s_nop 0
	v_pk_add_f32 v[16:17], v[16:17], v[18:19]
	ds_bpermute_b32 v18, v20, v16
	ds_bpermute_b32 v19, v20, v17
	s_waitcnt lgkmcnt(0)
	v_pk_add_f32 v[16:17], v[16:17], v[18:19]
	ds_bpermute_b32 v18, v21, v16
	ds_bpermute_b32 v19, v21, v17
	s_waitcnt lgkmcnt(0)
	v_pk_add_f32 v[16:17], v[16:17], v[18:19]
	s_nop 0
	v_pk_mul_f32 v[26:27], v[16:17], s[82:83] op_sel_hi:[1,0]
	v_lshl_add_u64 v[16:17], s[42:43], 0, v[22:23]
	global_load_dwordx4 v[16:19], v[16:17], off
	v_lshl_add_u64 v[22:23], s[46:47], 0, v[22:23]
	global_load_dwordx4 v[22:25], v[22:23], off
	v_fma_f32 v13, -v26, v26, v27
	v_max_f32_e32 v13, 0, v13
	v_add_f32_e32 v13, 0x3727c5ac, v13
	v_rsq_f32_e32 v28, v13
	s_waitcnt vmcnt(1)
	v_xor_b32_e32 v19, 0x80000000, v19
	v_xor_b32_e32 v18, 0x80000000, v18
	v_pk_fma_f32 v[6:7], v[18:19], v[26:27], v[6:7] op_sel_hi:[1,0,1]
	v_pk_fma_f32 v[4:5], v[16:17], v[26:27], v[4:5] op_sel_hi:[1,0,1] neg_lo:[1,0,0] neg_hi:[1,0,0]
	s_waitcnt vmcnt(0)
	v_pk_fma_f32 v[6:7], v[6:7], v[28:29], v[24:25] op_sel_hi:[1,0,1]
	v_pk_fma_f32 v[4:5], v[4:5], v[28:29], v[22:23] op_sel_hi:[1,0,1]
	v_max_f32_e32 v6, 0, v6
	v_max_f32_e32 v4, 0, v4
	v_max_f32_e32 v5, 0, v5
	v_max_f32_e32 v7, 0, v7
	v_pk_mul_f32 v[6:7], v[6:7], v[6:7]
	v_pk_mul_f32 v[4:5], v[4:5], v[4:5]
	s_nop 0
	v_cvt_pk_bf16_f32 v4, v4, v5
	v_cvt_pk_bf16_f32 v5, v6, v7
	v_lshl_add_u64 v[6:7], v[50:51], 1, v[8:9]
	global_store_dwordx2 v[6:7], v[4:5], off
	s_cbranch_scc0 .LBB0_2305

; template <int KSPLIT, class F>
; __device__ __forceinline__ void skinny_gemm(const bf16_t* A, const bf16_t* Bt, int N, int K, const F& f, LAS unsigned char* lds, int bx, int G, int wave) {
;     ...
;     for (int t = bx; t < ntiles; t += G) {
;         const int rg = t % RG, n0 = (t / RG) * 16;
;         const int mt = rg * MTW + (wave % MTW), kq = wave / MTW;
;         const bf16_t* ap = A + (size_t)(MP + 16 * mt + fr) * K + kq * klen + 8 * fq;
;         const bf16_t* bp = Bt + (size_t)(n0 + fr) * K + kq * klen + 8 * fq;
;         f32x4 acc = (f32x4){0.f, 0.f, 0.f, 0.f};
; #pragma unroll 16
;         for (int k = 0; k < klen; k += 32) {
;             const bf16x8 af = *(const bf16x8*)(ap + k), bf = *(const bf16x8*)(bp + k);
;             acc = __builtin_amdgcn_mfma_f32_16x16x32_bf16(bf, af, acc, 0, 0, 0);
;         }
.LBB0_2402:
	v_readlane_b32 s100, v251, 60
	s_mul_i32 s100, s100, 0x3000
	s_add_i32 s100, s100, 0x2000
	v_lshrrev_b32_e32 v202, 2, v219
	v_and_b32_e32 v203, 15, v219
	v_lshrrev_b32_e32 v201, 4, v219
	v_sub_u32_e32 v202, v202, v203
	v_lshlrev_b32_e32 v202, 13, v202
	v_and_b32_e32 v204, 3, v219
	v_xor_b32_e32 v204, v204, v201
	v_sub_u32_e32 v204, v204, v201
	v_lshl_add_u32 v202, v204, 4, v202
	v_lshrrev_b32_e32 v204, 2, v203
	v_xor_b32_e32 v204, v204, v201
	v_lshlrev_b32_e32 v200, 6, v203
	v_lshl_add_u32 v200, v204, 4, v200
	v_add_u32_e32 v200, s100, v200
	v_ashrrev_i32_e32 v203, 31, v202
	v_lshl_add_u64 v[196:197], v[202:203], 0, v[16:17]
	v_lshl_add_u64 v[198:199], v[202:203], 0, v[14:15]
	s_add_i32 m0, s100, 512
	s_nop 0
	global_load_lds_dwordx4 v[196:197], off offset:-512
	s_add_i32 m0, s100, 1536
	s_nop 0
	global_load_lds_dwordx4 v[198:199], off offset:-512
	s_add_i32 m0, s100, 2496
	s_nop 0
	global_load_lds_dwordx4 v[196:197], off offset:-448
	s_add_i32 m0, s100, 3520
	s_nop 0
	global_load_lds_dwordx4 v[198:199], off offset:-448
	s_add_i32 m0, s100, 4480
	s_nop 0
	global_load_lds_dwordx4 v[196:197], off offset:-384
	s_add_i32 m0, s100, 5504
	s_nop 0
	global_load_lds_dwordx4 v[198:199], off offset:-384
	s_add_i32 m0, s100, 6464
	s_nop 0
	global_load_lds_dwordx4 v[196:197], off offset:-320
	s_add_i32 m0, s100, 7488
	s_nop 0
	global_load_lds_dwordx4 v[198:199], off offset:-320
	s_add_i32 m0, s100, 8448
	s_nop 0
	global_load_lds_dwordx4 v[196:197], off offset:-256
	s_add_i32 m0, s100, 9472
	s_nop 0
	global_load_lds_dwordx4 v[198:199], off offset:-256
	s_add_i32 m0, s100, 10432
	s_nop 0
	global_load_lds_dwordx4 v[196:197], off offset:-192
	s_add_i32 m0, s100, 11456
	s_nop 0
	global_load_lds_dwordx4 v[198:199], off offset:-192
	s_waitcnt vmcnt(10)
	ds_read_b128 v[180:183], v200 offset:0
	ds_read_b128 v[184:187], v200 offset:1024
	s_waitcnt vmcnt(8)
	ds_read_b128 v[188:191], v200 offset:2048
	ds_read_b128 v[192:195], v200 offset:3072
	s_waitcnt lgkmcnt(2)
	v_mfma_f32_16x16x32_bf16 v[4:7], v[184:187], v[180:183], v[4:7]
	s_add_i32 m0, s100, 128
	s_nop 0
	global_load_lds_dwordx4 v[196:197], off offset:-128
	s_add_i32 m0, s100, 1152
	s_nop 0
	global_load_lds_dwordx4 v[198:199], off offset:-128
	s_waitcnt vmcnt(8)
	ds_read_b128 v[180:183], v200 offset:4096
	ds_read_b128 v[184:187], v200 offset:5120
	s_waitcnt lgkmcnt(2)
	v_mfma_f32_16x16x32_bf16 v[4:7], v[192:195], v[188:191], v[4:7]
	s_add_i32 m0, s100, 2112
	s_nop 0
	global_load_lds_dwordx4 v[196:197], off offset:-64
	s_add_i32 m0, s100, 3136
	s_nop 0
	global_load_lds_dwordx4 v[198:199], off offset:-64
	s_waitcnt vmcnt(8)
	ds_read_b128 v[188:191], v200 offset:6144
	ds_read_b128 v[192:195], v200 offset:7168
	s_waitcnt lgkmcnt(2)
	v_mfma_f32_16x16x32_bf16 v[4:7], v[184:187], v[180:183], v[4:7]
	s_add_i32 m0, s100, 4096
	s_nop 0
	global_load_lds_dwordx4 v[196:197], off
	s_add_i32 m0, s100, 5120
	s_nop 0
	global_load_lds_dwordx4 v[198:199], off
	s_waitcnt vmcnt(8)
	ds_read_b128 v[180:183], v200 offset:8192
	ds_read_b128 v[184:187], v200 offset:9216
	s_waitcnt lgkmcnt(2)
	v_mfma_f32_16x16x32_bf16 v[4:7], v[192:195], v[188:191], v[4:7]
	s_add_i32 m0, s100, 6080
	s_nop 0
	global_load_lds_dwordx4 v[196:197], off offset:64
	s_add_i32 m0, s100, 7104
	s_nop 0
	global_load_lds_dwordx4 v[198:199], off offset:64
	s_waitcnt vmcnt(8)
	ds_read_b128 v[188:191], v200 offset:10240
	ds_read_b128 v[192:195], v200 offset:11264
	s_waitcnt lgkmcnt(2)
	v_mfma_f32_16x16x32_bf16 v[4:7], v[184:187], v[180:183], v[4:7]
	s_add_i32 m0, s100, 8064
	s_nop 0
	global_load_lds_dwordx4 v[196:197], off offset:128
	s_add_i32 m0, s100, 9088
	s_nop 0
	global_load_lds_dwordx4 v[198:199], off offset:128
	s_waitcnt vmcnt(8)
	ds_read_b128 v[180:183], v200 offset:0
	ds_read_b128 v[184:187], v200 offset:1024
	s_waitcnt lgkmcnt(2)
	v_mfma_f32_16x16x32_bf16 v[4:7], v[192:195], v[188:191], v[4:7]
	s_add_i32 m0, s100, 10048
	s_nop 0
	global_load_lds_dwordx4 v[196:197], off offset:192
	s_add_i32 m0, s100, 11072
	s_nop 0
	global_load_lds_dwordx4 v[198:199], off offset:192
	s_waitcnt vmcnt(8)
	ds_read_b128 v[188:191], v200 offset:2048
	ds_read_b128 v[192:195], v200 offset:3072
	s_waitcnt lgkmcnt(2)
	v_mfma_f32_16x16x32_bf16 v[4:7], v[184:187], v[180:183], v[4:7]
	s_add_i32 m0, s100, -256
	s_nop 0
	global_load_lds_dwordx4 v[196:197], off offset:256
	s_add_i32 m0, s100, 768
	s_nop 0
	global_load_lds_dwordx4 v[198:199], off offset:256
	s_waitcnt vmcnt(8)
	ds_read_b128 v[180:183], v200 offset:4096
	ds_read_b128 v[184:187], v200 offset:5120
	s_waitcnt lgkmcnt(2)
	v_mfma_f32_16x16x32_bf16 v[4:7], v[192:195], v[188:191], v[4:7]
	s_add_i32 m0, s100, 1728
	s_nop 0
	global_load_lds_dwordx4 v[196:197], off offset:320
	s_add_i32 m0, s100, 2752
	s_nop 0
	global_load_lds_dwordx4 v[198:199], off offset:320
	s_waitcnt vmcnt(8)
	ds_read_b128 v[188:191], v200 offset:6144
	ds_read_b128 v[192:195], v200 offset:7168
	s_waitcnt lgkmcnt(2)
	v_mfma_f32_16x16x32_bf16 v[4:7], v[184:187], v[180:183], v[4:7]
	s_add_i32 m0, s100, 3712
	s_nop 0
	global_load_lds_dwordx4 v[196:197], off offset:384
	s_add_i32 m0, s100, 4736
	s_nop 0
	global_load_lds_dwordx4 v[198:199], off offset:384
	s_waitcnt vmcnt(8)
	ds_read_b128 v[180:183], v200 offset:8192
	ds_read_b128 v[184:187], v200 offset:9216
	s_waitcnt lgkmcnt(2)
	v_mfma_f32_16x16x32_bf16 v[4:7], v[192:195], v[188:191], v[4:7]
	s_add_i32 m0, s100, 5696
	s_nop 0
	global_load_lds_dwordx4 v[196:197], off offset:448
	s_add_i32 m0, s100, 6720
	s_nop 0
	global_load_lds_dwordx4 v[198:199], off offset:448
	s_waitcnt vmcnt(8)
	ds_read_b128 v[188:191], v200 offset:10240
	ds_read_b128 v[192:195], v200 offset:11264
	s_waitcnt lgkmcnt(2)
; template <int KSPLIT, class F>
; __device__ __forceinline__ void skinny_gemm(const bf16_t* A, const bf16_t* Bt, int N, int K, const F& f, LAS unsigned char* lds, int bx, int G, int wave) {
;     ...
;         for (int k = 0; k < klen; k += 32) {
;             const bf16x8 af = *(const bf16x8*)(ap + k), bf = *(const bf16x8*)(bp + k);
;             acc = __builtin_amdgcn_mfma_f32_16x16x32_bf16(bf, af, acc, 0, 0, 0);
;         }
	v_mfma_f32_16x16x32_bf16 v[4:7], v[184:187], v[180:183], v[4:7]
	s_add_i32 m0, s100, 7680
	s_nop 0
	global_load_lds_dwordx4 v[196:197], off offset:512
	s_add_i32 m0, s100, 8704
	s_nop 0
	global_load_lds_dwordx4 v[198:199], off offset:512
	s_waitcnt vmcnt(8)
	ds_read_b128 v[180:183], v200 offset:0
	ds_read_b128 v[184:187], v200 offset:1024
	s_waitcnt lgkmcnt(2)
	v_mfma_f32_16x16x32_bf16 v[4:7], v[192:195], v[188:191], v[4:7]
	s_add_i32 m0, s100, 9664
	s_nop 0
	global_load_lds_dwordx4 v[196:197], off offset:576
	s_add_i32 m0, s100, 10688
	s_nop 0
	global_load_lds_dwordx4 v[198:199], off offset:576
	s_waitcnt vmcnt(8)
	ds_read_b128 v[188:191], v200 offset:2048
	ds_read_b128 v[192:195], v200 offset:3072
	s_waitcnt lgkmcnt(2)
	v_mfma_f32_16x16x32_bf16 v[4:7], v[184:187], v[180:183], v[4:7]
	s_add_i32 m0, s100, -640
	s_nop 0
	global_load_lds_dwordx4 v[196:197], off offset:640
	s_add_i32 m0, s100, 384
	s_nop 0
	global_load_lds_dwordx4 v[198:199], off offset:640
	s_waitcnt vmcnt(8)
	ds_read_b128 v[180:183], v200 offset:4096
	ds_read_b128 v[184:187], v200 offset:5120
	s_waitcnt lgkmcnt(2)
	v_mfma_f32_16x16x32_bf16 v[4:7], v[192:195], v[188:191], v[4:7]
	s_add_i32 m0, s100, 1344
	s_nop 0
	global_load_lds_dwordx4 v[196:197], off offset:704
	s_add_i32 m0, s100, 2368
	s_nop 0
	global_load_lds_dwordx4 v[198:199], off offset:704
	s_waitcnt vmcnt(8)
	ds_read_b128 v[188:191], v200 offset:6144
	ds_read_b128 v[192:195], v200 offset:7168
	s_waitcnt lgkmcnt(2)
	v_mfma_f32_16x16x32_bf16 v[4:7], v[184:187], v[180:183], v[4:7]
	s_add_i32 m0, s100, 3328
	s_nop 0
	global_load_lds_dwordx4 v[196:197], off offset:768
	s_add_i32 m0, s100, 4352
	s_nop 0
	global_load_lds_dwordx4 v[198:199], off offset:768
	s_waitcnt vmcnt(8)
	ds_read_b128 v[180:183], v200 offset:8192
	ds_read_b128 v[184:187], v200 offset:9216
	s_waitcnt lgkmcnt(2)
	v_mfma_f32_16x16x32_bf16 v[4:7], v[192:195], v[188:191], v[4:7]
	s_add_i32 m0, s100, 5312
	s_nop 0
	global_load_lds_dwordx4 v[196:197], off offset:832
	s_add_i32 m0, s100, 6336
	s_nop 0
	global_load_lds_dwordx4 v[198:199], off offset:832
	s_waitcnt vmcnt(8)
	ds_read_b128 v[188:191], v200 offset:10240
	ds_read_b128 v[192:195], v200 offset:11264
	s_waitcnt lgkmcnt(2)
	v_mfma_f32_16x16x32_bf16 v[4:7], v[184:187], v[180:183], v[4:7]
	s_add_i32 m0, s100, 7296
	s_nop 0
	global_load_lds_dwordx4 v[196:197], off offset:896
	s_add_i32 m0, s100, 8320
	s_nop 0
	global_load_lds_dwordx4 v[198:199], off offset:896
	s_waitcnt vmcnt(8)
	ds_read_b128 v[180:183], v200 offset:0
	ds_read_b128 v[184:187], v200 offset:1024
	s_waitcnt lgkmcnt(2)
	v_mfma_f32_16x16x32_bf16 v[4:7], v[192:195], v[188:191], v[4:7]
	s_add_i32 m0, s100, 9280
	s_nop 0
	global_load_lds_dwordx4 v[196:197], off offset:960
	s_add_i32 m0, s100, 10304
	s_nop 0
	global_load_lds_dwordx4 v[198:199], off offset:960
	s_waitcnt vmcnt(8)
	ds_read_b128 v[188:191], v200 offset:2048
	ds_read_b128 v[192:195], v200 offset:3072
	s_waitcnt lgkmcnt(2)
	v_mfma_f32_16x16x32_bf16 v[4:7], v[184:187], v[180:183], v[4:7]
	s_add_i32 m0, s100, -1024
	s_nop 0
	global_load_lds_dwordx4 v[196:197], off offset:1024
	s_add_i32 m0, s100, 0
	s_nop 0
	global_load_lds_dwordx4 v[198:199], off offset:1024
	s_waitcnt vmcnt(8)
	ds_read_b128 v[180:183], v200 offset:4096
	ds_read_b128 v[184:187], v200 offset:5120
	s_waitcnt lgkmcnt(2)
	v_mfma_f32_16x16x32_bf16 v[4:7], v[192:195], v[188:191], v[4:7]
	s_add_i32 m0, s100, 960
	s_nop 0
	global_load_lds_dwordx4 v[196:197], off offset:1088
	s_add_i32 m0, s100, 1984
	s_nop 0
	global_load_lds_dwordx4 v[198:199], off offset:1088
	s_waitcnt vmcnt(8)
	ds_read_b128 v[188:191], v200 offset:6144
	ds_read_b128 v[192:195], v200 offset:7168
	s_waitcnt lgkmcnt(2)
	v_mfma_f32_16x16x32_bf16 v[4:7], v[184:187], v[180:183], v[4:7]
	s_add_i32 m0, s100, 2944
	s_nop 0
	global_load_lds_dwordx4 v[196:197], off offset:1152
	s_add_i32 m0, s100, 3968
	s_nop 0
	global_load_lds_dwordx4 v[198:199], off offset:1152
	s_waitcnt vmcnt(8)
	ds_read_b128 v[180:183], v200 offset:8192
	ds_read_b128 v[184:187], v200 offset:9216
	s_waitcnt lgkmcnt(2)
	v_mfma_f32_16x16x32_bf16 v[4:7], v[192:195], v[188:191], v[4:7]
	s_add_i32 m0, s100, 4928
	s_nop 0
	global_load_lds_dwordx4 v[196:197], off offset:1216
	s_add_i32 m0, s100, 5952
	s_nop 0
	global_load_lds_dwordx4 v[198:199], off offset:1216
	s_waitcnt vmcnt(8)
	ds_read_b128 v[188:191], v200 offset:10240
	ds_read_b128 v[192:195], v200 offset:11264
	s_waitcnt lgkmcnt(2)
	v_mfma_f32_16x16x32_bf16 v[4:7], v[184:187], v[180:183], v[4:7]
	s_add_i32 m0, s100, 6912
	s_nop 0
	global_load_lds_dwordx4 v[196:197], off offset:1280
	s_add_i32 m0, s100, 7936
	s_nop 0
	global_load_lds_dwordx4 v[198:199], off offset:1280
	s_waitcnt vmcnt(8)
	ds_read_b128 v[180:183], v200 offset:0
	ds_read_b128 v[184:187], v200 offset:1024
	s_waitcnt lgkmcnt(2)
	v_mfma_f32_16x16x32_bf16 v[4:7], v[192:195], v[188:191], v[4:7]
	s_add_i32 m0, s100, 8896
	s_nop 0
	global_load_lds_dwordx4 v[196:197], off offset:1344
	s_add_i32 m0, s100, 9920
	s_nop 0
	global_load_lds_dwordx4 v[198:199], off offset:1344
	s_waitcnt vmcnt(8)
	ds_read_b128 v[188:191], v200 offset:2048
	ds_read_b128 v[192:195], v200 offset:3072
	s_waitcnt lgkmcnt(2)
	v_mfma_f32_16x16x32_bf16 v[4:7], v[184:187], v[180:183], v[4:7]
	s_add_i32 m0, s100, -1408
	s_nop 0
	global_load_lds_dwordx4 v[196:197], off offset:1408
	s_add_i32 m0, s100, -384
	s_nop 0
	global_load_lds_dwordx4 v[198:199], off offset:1408
	s_waitcnt vmcnt(8)
	ds_read_b128 v[180:183], v200 offset:4096
	ds_read_b128 v[184:187], v200 offset:5120
	s_waitcnt lgkmcnt(2)
	v_mfma_f32_16x16x32_bf16 v[4:7], v[192:195], v[188:191], v[4:7]
	s_add_i32 m0, s100, 576
	s_nop 0
	global_load_lds_dwordx4 v[196:197], off offset:1472
	s_add_i32 m0, s100, 1600
	s_nop 0
	global_load_lds_dwordx4 v[198:199], off offset:1472
	s_waitcnt vmcnt(8)
	ds_read_b128 v[188:191], v200 offset:6144
	ds_read_b128 v[192:195], v200 offset:7168
	s_waitcnt lgkmcnt(2)
	v_mfma_f32_16x16x32_bf16 v[4:7], v[184:187], v[180:183], v[4:7]
	s_waitcnt vmcnt(6)
	ds_read_b128 v[180:183], v200 offset:8192
	ds_read_b128 v[184:187], v200 offset:9216
	s_waitcnt lgkmcnt(2)
	v_mfma_f32_16x16x32_bf16 v[4:7], v[192:195], v[188:191], v[4:7]
	s_waitcnt vmcnt(4)
	ds_read_b128 v[188:191], v200 offset:10240
	ds_read_b128 v[192:195], v200 offset:11264
	s_waitcnt lgkmcnt(2)
	v_mfma_f32_16x16x32_bf16 v[4:7], v[184:187], v[180:183], v[4:7]
	s_waitcnt vmcnt(2)
	ds_read_b128 v[180:183], v200 offset:0
	ds_read_b128 v[184:187], v200 offset:1024
	s_waitcnt lgkmcnt(2)
	v_mfma_f32_16x16x32_bf16 v[4:7], v[192:195], v[188:191], v[4:7]
	s_waitcnt vmcnt(0)
	ds_read_b128 v[188:191], v200 offset:2048
	ds_read_b128 v[192:195], v200 offset:3072
	s_waitcnt lgkmcnt(2)
	v_mfma_f32_16x16x32_bf16 v[4:7], v[184:187], v[180:183], v[4:7]
	s_waitcnt lgkmcnt(0)
	v_mfma_f32_16x16x32_bf16 v[4:7], v[192:195], v[188:191], v[4:7]
	s_nop 0
	v_readlane_b32 s8, v253, 39
	v_readlane_b32 s9, v253, 40
	s_andn2_b64 vcc, exec, s[8:9]
	s_barrier
; #define LAS __attribute__((address_space(3)))
; __device__ __forceinline__ u32x2 pk4(f32x4 v) { u32x2 r; r.x = pk2(v.x, v.y); r.y = pk2(v.z, v.w); return r; }
;     __device__ __forceinline__ void sk(int row, int col, f32x4 v, int fq) const {
;         float mu = 0.f, rs = 1.f; if (ln) stats_sk(sts_p, row, fq, mu, rs);
;         const u32x2 raw = *(const u32x2*)(src + (size_t)row * DM + col);
;         f32x4 x = (f32x4){bflo(raw.x), bfhi(raw.x), bflo(raw.y), bfhi(raw.y)};
;         if (ln) x = (x - mu) * rs * *(const f32x4*)(g + col) + *(const f32x4*)(b + col);
;         const u32x2 pz = pk4(x * ALPHA + v);
;         *(u32x2*)(dst + (size_t)row * DM + col) = pz;
;         const float z0 = bflo(pz.x), z1 = bfhi(pz.x), z2 = bflo(pz.y), z3 = bfhi(pz.y);
;         float s1 = (z0 + z1) + (z2 + z3), s2 = (z0 * z0 + z1 * z1) + (z2 * z2 + z3 * z3);
;         s1 += __shfl_xor(s1, 16); s2 += __shfl_xor(s2, 16); s1 += __shfl_xor(s1, 32); s2 += __shfl_xor(s2, 32);
;         if (fq == 0) { float* p = sts_n + (size_t)(row - MP) * 128 + (col >> 4) * 2; p[0] = s1; p[1] = s2; }
; template <int KSPLIT, class F>
; __device__ __forceinline__ void skinny_gemm(const bf16_t* A, const bf16_t* Bt, int N, int K, const F& f, LAS unsigned char* lds, int bx, int G, int wave) {
;     ...
;         if (KSPLIT > 1) {
;             __syncthreads();
;             *(LAS f32x4*)(lds + wave * 1024 + lane * 16) = acc;
;             __syncthreads();
;             if (kq == 0) {
; #pragma unroll
;                 for (int q = 1; q < KSPLIT; ++q) acc = acc + *(const LAS f32x4*)(lds + (wave + q * MTW) * 1024 + lane * 16);
;                 f.sk(MP + 16 * mt + fr, n0 + 4 * fq, acc, fq);
	s_nop 2
	ds_write_b128 v24, v[4:7]
	s_waitcnt lgkmcnt(0)
	s_barrier
	s_cbranch_vccnz .LBB0_2400
	ds_read_b128 v[14:17], v24 offset:2048
	v_ashrrev_i32_e32 v13, 31, v12
	s_waitcnt lgkmcnt(0)
	v_pk_add_f32 v[16:17], v[6:7], v[16:17]
	v_pk_add_f32 v[14:15], v[4:5], v[14:15]
	ds_read_b128 v[4:7], v24 offset:4096
	s_waitcnt lgkmcnt(0)
	v_pk_add_f32 v[6:7], v[16:17], v[6:7]
	v_pk_add_f32 v[18:19], v[14:15], v[4:5]
	ds_read_b128 v[14:17], v24 offset:6144
	s_waitcnt lgkmcnt(0)
	v_pk_add_f32 v[4:5], v[6:7], v[16:17]
	v_add_u32_e32 v16, s0, v23
	s_mov_b32 s0, 0xff800000
	v_pk_add_f32 v[6:7], v[18:19], v[14:15]
	v_lshlrev_b64 v[14:15], 9, v[12:13]
	s_mov_b32 s1, -1
	v_lshl_add_u64 v[14:15], v[14:15], 0, s[0:1]
	v_lshl_add_u64 v[26:27], v[0:1], 0, v[14:15]
	global_load_dwordx4 v[18:21], v[26:27], off offset:48
	global_load_dwordx4 v[28:31], v[26:27], off offset:32
	global_load_dwordx4 v[32:35], v[26:27], off offset:16
	global_load_dwordx4 v[36:39], v[26:27], off
	global_load_dwordx4 v[40:43], v[26:27], off offset:112
	global_load_dwordx4 v[44:47], v[26:27], off offset:96
	global_load_dwordx4 v[48:51], v[26:27], off offset:80
	global_load_dwordx4 v[52:55], v[26:27], off offset:64
	v_and_b32_e32 v17, 64, v219
	v_xor_b32_e32 v13, 16, v219
	v_add_u32_e32 v17, 64, v17
	v_cmp_lt_i32_e32 vcc, v13, v17
	v_lshlrev_b32_e32 v12, 11, v12
	s_waitcnt vmcnt(7)
	v_pk_add_f32 v[18:19], v[18:19], v[20:21]
	s_waitcnt vmcnt(6)
	v_pk_add_f32 v[28:29], v[28:29], v[30:31]
	s_waitcnt vmcnt(5)
	v_pk_add_f32 v[32:33], v[32:33], v[34:35]
	s_waitcnt vmcnt(4)
	v_pk_add_f32 v[36:37], v[36:37], v[38:39]
	v_cndmask_b32_e32 v13, v219, v13, vcc
	v_pk_add_f32 v[36:37], v[36:37], 0 op_sel_hi:[1,0]
	v_lshlrev_b32_e32 v26, 2, v13
	v_pk_add_f32 v[32:33], v[36:37], v[32:33]
	s_waitcnt vmcnt(0)
	v_pk_add_f32 v[20:21], v[52:53], v[54:55]
	v_pk_add_f32 v[28:29], v[32:33], v[28:29]
	v_xor_b32_e32 v13, 32, v219
	v_pk_add_f32 v[18:19], v[28:29], v[18:19]
	v_cmp_lt_i32_e32 vcc, v13, v17
	v_pk_add_f32 v[18:19], v[18:19], v[20:21]
	v_pk_add_f32 v[20:21], v[48:49], v[50:51]
	v_cndmask_b32_e32 v13, v219, v13, vcc
	v_pk_add_f32 v[18:19], v[18:19], v[20:21]
	v_pk_add_f32 v[20:21], v[44:45], v[46:47]
	v_lshlrev_b32_e32 v25, 2, v13
	v_pk_add_f32 v[18:19], v[18:19], v[20:21]
	v_pk_add_f32 v[20:21], v[40:41], v[42:43]
	v_ashrrev_i32_e32 v17, 31, v16
	v_pk_add_f32 v[18:19], v[18:19], v[20:21]
	ds_bpermute_b32 v20, v26, v18
	ds_bpermute_b32 v21, v26, v19
	s_waitcnt lgkmcnt(0)
	v_pk_add_f32 v[18:19], v[18:19], v[20:21]
	ds_bpermute_b32 v20, v25, v18
	ds_bpermute_b32 v21, v25, v19
	s_waitcnt lgkmcnt(0)
	v_pk_add_f32 v[18:19], v[18:19], v[20:21]
	s_nop 0
	v_pk_mul_f32 v[18:19], v[18:19], s[82:83] op_sel_hi:[1,0]
	s_nop 0
	v_fma_f32 v13, -v18, v18, v19
	v_max_f32_e32 v13, 0, v13
	v_add_f32_e32 v13, 0x3727c5ac, v13
	v_rsq_f32_e32 v20, v13
	v_mov_b32_e32 v13, v2
	v_lshl_add_u64 v[12:13], s[70:71], 0, v[12:13]
	v_lshl_add_u64 v[12:13], v[16:17], 1, v[12:13]
	global_load_dwordx2 v[28:29], v[12:13], off
	v_lshlrev_b64 v[16:17], 2, v[16:17]
	s_waitcnt vmcnt(0)
	v_lshlrev_b32_e32 v19, 16, v28
	v_and_b32_e32 v21, 0xffff0000, v28
	v_lshlrev_b32_e32 v27, 16, v29
	v_and_b32_e32 v30, 0xffff0000, v29
	v_sub_f32_e32 v29, v21, v18
	v_sub_f32_e32 v28, v19, v18
	v_sub_f32_e32 v19, v30, v18
	v_sub_f32_e32 v18, v27, v18
	v_pk_mul_f32 v[18:19], v[20:21], v[18:19] op_sel_hi:[0,1]
	v_pk_mul_f32 v[20:21], v[20:21], v[28:29] op_sel_hi:[0,1]
	v_lshl_add_u64 v[28:29], s[46:47], 0, v[16:17]
	v_lshl_add_u64 v[16:17], s[48:49], 0, v[16:17]
	global_load_dwordx4 v[28:31], v[28:29], off
	s_nop 0
	global_load_dwordx4 v[32:35], v[16:17], off
	s_waitcnt vmcnt(0)
	v_pk_fma_f32 v[16:17], v[28:29], v[20:21], v[32:33]
	v_pk_fma_f32 v[18:19], v[30:31], v[18:19], v[34:35]
	v_pk_fma_f32 v[6:7], v[16:17], s[72:73], v[6:7] op_sel_hi:[1,0,1]
	v_pk_fma_f32 v[4:5], v[18:19], s[72:73], v[4:5] op_sel_hi:[1,0,1]
	v_cvt_pk_bf16_f32 v6, v6, v7
	v_cvt_pk_bf16_f32 v7, v4, v5
	global_store_dwordx2 v[12:13], v[6:7], off
	v_lshlrev_b32_e32 v4, 16, v6
	v_and_b32_e32 v6, 0xffff0000, v6
	v_lshlrev_b32_e32 v12, 16, v7
	v_and_b32_e32 v16, 0xffff0000, v7
	v_mul_f32_e32 v5, v4, v4
	v_mul_f32_e32 v7, v6, v6
	v_mul_f32_e32 v13, v12, v12
	v_mul_f32_e32 v17, v16, v16
	v_pk_add_f32 v[4:5], v[4:5], v[6:7]
	v_pk_add_f32 v[6:7], v[12:13], v[16:17]
	s_nop 0
	v_pk_add_f32 v[4:5], v[4:5], v[6:7]
	ds_bpermute_b32 v6, v26, v4
	ds_bpermute_b32 v7, v26, v5
	s_waitcnt lgkmcnt(0)
	v_pk_add_f32 v[4:5], v[4:5], v[6:7]
	ds_bpermute_b32 v6, v25, v4
	ds_bpermute_b32 v7, v25, v5
	s_and_saveexec_b64 s[0:1], s[36:37]
	s_cbranch_execz .LBB0_2399
	s_lshl_b32 s8, s4, 1
	v_lshl_add_u64 v[12:13], s[38:39], 0, v[14:15]
	s_ashr_i32 s9, s8, 31
	v_lshl_add_u64 v[12:13], s[8:9], 2, v[12:13]
	s_waitcnt lgkmcnt(0)
	v_pk_add_f32 v[4:5], v[4:5], v[6:7]
	global_store_dwordx2 v[12:13], v[4:5], off
	s_branch .LBB0_2399

; __global__ void __launch_bounds__(NWAVES * 64, 2) mega(Args args) {
	.amdhsa_kernel _Z4mega4Args
		.amdhsa_group_segment_fixed_size 0
		.amdhsa_private_segment_fixed_size 0
		.amdhsa_kernarg_size 472
		.amdhsa_user_sgpr_count 2
		.amdhsa_user_sgpr_dispatch_ptr 0
		.amdhsa_user_sgpr_queue_ptr 0
		.amdhsa_user_sgpr_kernarg_segment_ptr 1
		.amdhsa_user_sgpr_dispatch_id 0
		.amdhsa_user_sgpr_kernarg_preload_length 0
		.amdhsa_user_sgpr_kernarg_preload_offset 0
		.amdhsa_user_sgpr_private_segment_size 0
		.amdhsa_uses_dynamic_stack 0
		.amdhsa_enable_private_segment 0
		.amdhsa_system_sgpr_workgroup_id_x 1
		.amdhsa_system_sgpr_workgroup_id_y 0
		.amdhsa_system_sgpr_workgroup_id_z 0
		.amdhsa_system_sgpr_workgroup_info 0
		.amdhsa_system_vgpr_workitem_id 2
		.amdhsa_next_free_vgpr 256
		.amdhsa_next_free_sgpr 102
		.amdhsa_accum_offset 256
		.amdhsa_reserve_vcc 1
		.amdhsa_float_round_mode_32 0
		.amdhsa_float_round_mode_16_64 0
		.amdhsa_float_denorm_mode_32 3
		.amdhsa_float_denorm_mode_16_64 3
		.amdhsa_dx10_clamp 1
		.amdhsa_ieee_mode 1
		.amdhsa_fp16_overflow 0
		.amdhsa_tg_split 0
		.amdhsa_exception_fp_ieee_invalid_op 0
		.amdhsa_exception_fp_denorm_src 0
		.amdhsa_exception_fp_ieee_div_zero 0
		.amdhsa_exception_fp_ieee_overflow 0
		.amdhsa_exception_fp_ieee_underflow 0
		.amdhsa_exception_fp_ieee_inexact 0
		.amdhsa_exception_int_div_zero 0
	.end_amdhsa_kernel

; __global__ void __launch_bounds__(NWAVES * 64, 2) mega(Args args) {
amdhsa.kernels:
  - .agpr_count:     0
    .args:
      - .offset:         0
        .size:           216
        .value_kind:     by_value
      - .offset:         216
        .size:           4
        .value_kind:     hidden_block_count_x
      - .offset:         220
        .size:           4
        .value_kind:     hidden_block_count_y
      - .offset:         224
        .size:           4
        .value_kind:     hidden_block_count_z
      - .offset:         228
        .size:           2
        .value_kind:     hidden_group_size_x
      - .offset:         230
        .size:           2
        .value_kind:     hidden_group_size_y
      - .offset:         232
        .size:           2
        .value_kind:     hidden_group_size_z
      - .offset:         234
        .size:           2
        .value_kind:     hidden_remainder_x
      - .offset:         236
        .size:           2
        .value_kind:     hidden_remainder_y
      - .offset:         238
        .size:           2
        .value_kind:     hidden_remainder_z
      - .offset:         256
        .size:           8
        .value_kind:     hidden_global_offset_x
      - .offset:         264
        .size:           8
        .value_kind:     hidden_global_offset_y
      - .offset:         272
        .size:           8
        .value_kind:     hidden_global_offset_z
      - .offset:         280
        .size:           2
        .value_kind:     hidden_grid_dims
      - .offset:         304
        .size:           8
        .value_kind:     hidden_multigrid_sync_arg
      - .offset:         336
        .size:           4
        .value_kind:     hidden_dynamic_lds_size
    .group_segment_fixed_size: 0
    .kernarg_segment_align: 8
    .kernarg_segment_size: 472
    .language:       OpenCL C
    .language_version:
      - 2
      - 0
    .max_flat_workgroup_size: 512
    .name:           _Z4mega4Args
    .private_segment_fixed_size: 0
    .sgpr_count:     108
    .sgpr_spill_count: 319
    .symbol:         _Z4mega4Args.kd
    .uniform_work_group_size: 1
    .uses_dynamic_stack: false
    .vgpr_count:     256
    .vgpr_spill_count: 0
    .wavefront_size: 64
